# P4 EpiConv rewritten by hand: A-operand DMA rows interleaved (acc row = 4*fr+m) so conv neighbours are in-lane, pair-interleaved conv table with log2e folded in
# speedup vs baseline: 1.0213x; 1.0213x over previous
; __global__ void __launch_bounds__(NTHREADS, 2) hymba_fwd(Args args) {
;     ...
;         for (int i = bx * NTHREADS + tid; i < 2 * DFF; i += G * NTHREADS) { const int l = i / DFF, c = i - l * DFF; const float* w = ap_->in[I_CW] + (size_t)l * 3 * NUP; const float* b = ap_->in[I_CB] + (size_t)l * NUP;
;             f32x4 a = {w[c], w[NUP + c], w[2 * NUP + c], b[c]}, g = {w[DFF + c], w[NUP + DFF + c], w[2 * NUP + DFF + c], b[DFF + c]}; *(f32x4*)(CT + (size_t)i * 8) = a; *(f32x4*)(CT + (size_t)i * 8 + 4) = g; }
.LBB0_92:
	v_lshl_add_u32 v2, s97, 9, v31
	s_movk_i32 s4, 0x1600
	v_cmp_gt_i32_e32 vcc, s4, v2
	s_and_saveexec_b64 s[8:9], vcc
	s_cbranch_execz .LBB0_95
	s_load_dwordx4 s[4:7], s[2:3], 0xc0
	v_ashrrev_i32_e32 v3, 31, v2
	s_lshl_b32 s12, s80, 9
	v_lshlrev_b64 v[4:5], 5, v[2:3]
	s_waitcnt lgkmcnt(0)
	v_lshl_add_u64 v[4:5], s[10:11], 0, v[4:5]
	s_mov_b64 s[14:15], 0x3500000
	s_ashr_i32 s13, s12, 31
	v_lshl_add_u64 v[4:5], v[4:5], 0, s[14:15]
	v_and_b32_e32 v6, 1, v2
	v_mul_u32_u24_e32 v6, 28, v6
	v_sub_co_u32_e32 v4, vcc, v4, v6
	s_nop 1
	v_subbrev_co_u32_e32 v5, vcc, 0, v5, vcc
	s_lshl_b64 s[14:15], s[12:13], 5
	s_mov_b64 s[16:17], 0
	s_mov_b32 s13, 0x2e8ba2e9
	s_movk_i32 s18, 0xf500
	s_movk_i32 s19, 0x5000
	s_mov_b32 s20, 0xb000
	s_movk_i32 s21, 0x2000
	s_mov_b32 s22, 0x8000
	s_mov_b32 s23, 0xd000
	s_movk_i32 s24, 0x15ff
.LBB0_94:
	v_mul_hi_i32 v1, v2, s13
	v_lshrrev_b32_e32 v3, 31, v1
	v_ashrrev_i32_e32 v1, 9, v1
	v_add_u32_e32 v1, v1, v3
	v_mad_i32_i24 v6, v1, s18, v2
	v_mul_hi_i32_i24_e32 v9, 0x10800, v1
	v_mul_i32_i24_e32 v8, 0x10800, v1
	v_ashrrev_i32_e32 v7, 31, v6
	v_lshl_add_u64 v[8:9], s[4:5], 0, v[8:9]
	v_lshlrev_b64 v[6:7], 2, v[6:7]
	v_lshl_add_u64 v[12:13], v[8:9], 0, v[6:7]
	v_add_co_u32_e32 v16, vcc, s19, v12
	v_mul_hi_i32_i24_e32 v11, 0x5800, v1
	s_nop 0
	v_addc_co_u32_e32 v17, vcc, 0, v13, vcc
	v_add_co_u32_e32 v18, vcc, s20, v12
	v_mul_i32_i24_e32 v10, 0x5800, v1
	s_nop 0
	v_addc_co_u32_e32 v19, vcc, 0, v13, vcc
	v_add_co_u32_e32 v20, vcc, s21, v12
	v_lshl_add_u64 v[10:11], s[6:7], 0, v[10:11]
	s_nop 0
	v_addc_co_u32_e32 v21, vcc, 0, v13, vcc
	v_add_co_u32_e32 v22, vcc, s22, v12
	v_lshl_add_u64 v[14:15], v[10:11], 0, v[6:7]
	s_nop 0
	v_addc_co_u32_e32 v23, vcc, 0, v13, vcc
	global_load_dword v9, v[14:15], off
	global_load_dword v6, v[12:13], off
	global_load_dword v7, v[16:17], off offset:2048
	global_load_dword v8, v[18:19], off
	global_load_dword v10, v[20:21], off offset:3072
	v_add_co_u32_e32 v16, vcc, s23, v12
	v_add_u32_e32 v2, s12, v2
	s_nop 0
	v_addc_co_u32_e32 v17, vcc, 0, v13, vcc
	v_add_co_u32_e32 v14, vcc, s21, v14
	global_load_dword v11, v[22:23], off offset:1024
	global_load_dword v12, v[16:17], off offset:3072
	v_addc_co_u32_e32 v15, vcc, 0, v15, vcc
	global_load_dword v13, v[14:15], off offset:3072
	v_cmp_lt_i32_e32 vcc, s24, v2
	s_or_b64 s[16:17], vcc, s[16:17]
	s_waitcnt vmcnt(4)
	v_mul_f32_e32 v6, 0x3f317218, v6
	v_mul_f32_e32 v7, 0x3f317218, v7
	v_mul_f32_e32 v8, 0x3f317218, v8
	v_mul_f32_e32 v9, 0x3f317218, v9
	global_store_dword v[4:5], v6, off
	global_store_dword v[4:5], v7, off offset:8
	global_store_dword v[4:5], v8, off offset:16
	global_store_dword v[4:5], v9, off offset:24
	s_waitcnt vmcnt(4)
	v_mul_f32_e32 v10, 0x3fb8aa3b, v10
	v_mul_f32_e32 v11, 0x3fb8aa3b, v11
	v_mul_f32_e32 v12, 0x3fb8aa3b, v12
	v_mul_f32_e32 v13, 0x3fb8aa3b, v13
	global_store_dword v[4:5], v10, off offset:32
	global_store_dword v[4:5], v11, off offset:40
	global_store_dword v[4:5], v12, off offset:48
	global_store_dword v[4:5], v13, off offset:56
	v_lshl_add_u64 v[4:5], v[4:5], 0, s[14:15]
	s_andn2_b64 exec, exec, s[16:17]
	s_cbranch_execnz .LBB0_94

; #define PG8_ABASE(pm_) (HALO ? ((const char*)Ag + ((long)halo_row0(pm_)) * (long)K * 2) : ((const char*)Ag + (size_t)(pm_) * 2 * hstepB))
; #define PG8_STAGE(bufoff, gbase, voff) do { _Pragma("unroll") for (int _i = 0; _i < 2; ++_i) \
;         __builtin_amdgcn_global_load_lds((const unsigned*)((const char*)(gbase) + (voff)[_i]), (LAS unsigned*)(lds + (bufoff) + ldsw + _i * 8192), 16, 0, 0); } while (0)
; #define PG8_WAIT_V(n) asm volatile("s_waitcnt vmcnt(" #n ")" ::: "memory")
; #define PG8_BAR __builtin_amdgcn_s_barrier()
; template <class Epi, bool HALO>
; __device__ __forceinline__ void gemm_phase(LAS unsigned char* lds, const bf16_t* Ag, const bf16_t* Btg, const int K, const int nM, const int nN, const int G, const int cidx, const int wave_, const Epi& E) {
;     ...
;     for (int i = 0; i < 2; ++i) { int R, C; stage_rc(tid * 16 + i * 8192, R, C); const int Rb = (R & ~31) + perm32(R & 31);
;         const int Ra = HALO ? (R - 2 * (R >> 6)) : R;
;         voffA[i] = (unsigned)(Ra * K + C) * 2u; voffB[i] = (unsigned)(Rb * K + C) * 2u; }
;     ...
;     const char* cA = PG8_ABASE(cur.pm); const char* cB = PG8_BBASE(cur.pn);
;     PG8_STAGE(PG8_SB(0, 0), cB, voffB); PG8_STAGE(PG8_SB(0, 1), cB + hstepB, voffB); PG8_STAGE(PG8_SA(0, 0), cA, voffA); PG8_STAGE(PG8_SA(0, 1), cA + hstepA, voffA);
;     if (wr == 1) PG8_BAR;
;     PG8_WAIT_V(2); PG8_BAR;
;     PG8_STAGE(PG8_SB(1, 0), cB + kstep, voffB); PG8_STAGE(PG8_SA(1, 0), cA + kstep, voffA); PG8_STAGE(PG8_SB(1, 1), cB + hstepB + kstep, voffB);
;     PG8_WAIT_V(6); PG8_BAR;
.LBB0_772:
	s_or_b64 exec, exec, s[2:3]
	v_readlane_b32 s2, v254, 0
	v_readlane_b32 s3, v254, 1
	s_waitcnt lgkmcnt(0)
	v_mov_b32_e32 v0, v145
	s_barrier
	v_readlane_b32 s0, v254, 17
	v_mbcnt_lo_u32_b32 v0, -1, v0
	v_mbcnt_hi_u32_b32 v0, -1, v0
	v_add_u32_e32 v9, s81, v0
	v_readlane_b32 s1, v254, 18
	s_andn2_b64 vcc, exec, s[0:1]
	v_readfirstlane_b32 s4, v9
	s_cbranch_vccnz .LBB0_814
	v_lshlrev_b32_e32 v0, 4, v9
	v_add_u32_e32 v1, 0x2000, v0
	v_ashrrev_i32_e32 v2, 31, v1
	v_lshrrev_b32_e32 v2, 22, v2
	v_add_u32_e32 v2, v1, v2
	v_ashrrev_i32_e32 v8, 10, v2
	s_load_dwordx2 s[12:13], s[2:3], 0xe0
	v_mul_i32_i24_e32 v2, 0x400, v8
	v_sub_u32_e32 v1, v1, v2
	v_lshrrev_b32_e32 v2, 4, v1
	v_bitop3_b32 v1, v2, v1, 32 bitop3:0x6c
	v_ashrrev_i32_e32 v2, 31, v1
	s_waitcnt lgkmcnt(0)
	s_add_u32 s0, s12, 0x4100000
	v_lshrrev_b32_e32 v2, 26, v2
	s_addc_u32 s1, s13, 0
	v_readlane_b32 s2, v255, 6
	v_add_u32_e32 v2, v1, v2
	v_lshlrev_b32_e32 v4, 3, v8
	s_add_u32 s2, s12, s2
	v_ashrrev_i32_e32 v3, 6, v2
	v_and_b32_e32 v4, -16, v4
	s_addc_u32 s3, s13, 0
	v_add_u32_e32 v4, v3, v4
	s_add_u32 s38, s2, 0x700000
	v_and_b32_e32 v3, 3, v3
	s_mov_b32 s2, 0x1fffe0
	v_lshrrev_b32_e32 v5, 2, v4
	v_lshlrev_b32_e32 v6, 1, v4
	v_and_b32_e32 v2, 0xc0, v2
	v_and_or_b32 v3, v4, s2, v3
	v_and_b32_e32 v5, 4, v5
	v_and_b32_e32 v6, 24, v6
	v_sub_u32_e32 v1, v1, v2
	v_lshrrev_b32_e32 v2, 5, v4
	v_or3_b32 v3, v3, v5, v6
	v_lshlrev_b32_e32 v5, 5, v8
	v_ashrrev_i16_sdwa v1, v184, sext(v1) dst_sel:DWORD dst_unused:UNUSED_PAD src0_sel:DWORD src1_sel:BYTE_0
	v_and_b32_e32 v2, 0x1ffffe, v2
	v_and_b32_e32 v5, 32, v5
	v_bfe_i32 v10, v1, 0, 16
	v_and_b32_e32 v250, 15, v4
	v_bfe_u32 v251, v4, 4, 2
	v_lshl_or_b32 v250, v250, 2, v251
	v_and_b32_e32 v251, 0xffffffc0, v4
	v_or_b32_e32 v250, v250, v251
	v_sub_u32_e32 v2, v250, v2
	v_add_lshl_u32 v1, v5, v10, 1
	v_lshlrev_b32_e32 v11, 11, v2
	v_lshl_add_u32 v152, v3, 11, v1
	v_add_u32_e32 v154, v11, v1
	v_bfe_i32 v1, v9, 27, 1
	v_lshrrev_b32_e32 v1, 22, v1
	v_add_u32_e32 v1, v0, v1
	v_and_b32_e32 v1, 0xfffffc00, v1
	v_sub_u32_e32 v0, v0, v1
	v_lshrrev_b32_e32 v1, 4, v0
	v_ashrrev_i32_e32 v3, 31, v9
	v_bitop3_b32 v0, v1, v0, 32 bitop3:0x6c
	v_lshrrev_b32_e32 v3, 26, v3
	v_ashrrev_i32_e32 v1, 31, v0
	v_add_u32_e32 v3, v9, v3
	v_lshrrev_b32_e32 v1, 26, v1
	v_ashrrev_i32_e32 v12, 6, v3
	v_add_u32_e32 v1, v0, v1
	v_lshlrev_b32_e32 v3, 3, v12
	v_ashrrev_i32_e32 v2, 6, v1
	v_and_b32_e32 v3, -16, v3
	v_add_u32_e32 v3, v2, v3
	v_and_b32_e32 v2, 3, v2
	v_lshrrev_b32_e32 v4, 2, v3
	v_lshlrev_b32_e32 v5, 1, v3
	v_and_b32_e32 v1, 0xc0, v1
	s_addc_u32 s39, s3, 0
	s_ashr_i32 s5, s4, 6
	v_and_or_b32 v2, v3, s2, v2
	v_and_b32_e32 v4, 4, v4
	v_and_b32_e32 v5, 24, v5
	v_sub_u32_e32 v0, v0, v1
	s_ashr_i32 s8, s4, 8
	s_lshl_b32 s40, s5, 10
	v_or3_b32 v2, v2, v4, v5
	v_lshlrev_b32_e32 v4, 5, v12
	v_ashrrev_i16_sdwa v0, v184, sext(v0) dst_sel:DWORD dst_unused:UNUSED_PAD src0_sel:DWORD src1_sel:BYTE_0
	v_readlane_b32 s2, v254, 28
	v_and_b32_e32 v4, 32, v4
	v_bfe_i32 v13, v0, 0, 16
	v_readlane_b32 s3, v254, 29
	s_add_u32 s18, s38, s2
	v_add_lshl_u32 v0, v4, v13, 1
	s_addc_u32 s19, s39, s3
	s_add_i32 s41, s40, 0
	v_lshl_add_u32 v156, v2, 11, v0
	s_add_i32 m0, s41, 0x10000
	v_lshrrev_b32_e32 v1, 5, v3
	global_load_lds_dwordx4 v156, s[18:19]
	s_add_i32 m0, s41, 0x12000
	s_add_u32 s2, s18, 0x40000
	global_load_lds_dwordx4 v152, s[18:19]
	s_addc_u32 s3, s19, 0
	s_add_i32 m0, s41, 0x14000
	v_and_b32_e32 v1, 0x1ffffe, v1
	global_load_lds_dwordx4 v156, s[2:3]
	s_add_i32 m0, s41, 0x16000
	v_and_b32_e32 v250, 15, v3
	v_bfe_u32 v251, v3, 4, 2
	v_lshl_or_b32 v250, v250, 2, v251
	v_and_b32_e32 v251, 0xffffffc0, v3
	v_or_b32_e32 v250, v250, v251
	v_sub_u32_e32 v1, v250, v1
	global_load_lds_dwordx4 v152, s[2:3]
	v_readlane_b32 s2, v254, 43
	s_add_u32 s2, s0, s2
	v_readlane_b32 s3, v254, 44
	v_lshlrev_b32_e32 v14, 11, v1
	s_addc_u32 s3, s1, s3
	s_add_i32 s42, s41, 0x2000
	v_add_u32_e32 v158, v14, v0
	s_mov_b32 m0, s41
	s_add_u32 s6, s2, 0x3e000
	global_load_lds_dwordx4 v158, s[2:3]
	s_mov_b32 m0, s42
	s_addc_u32 s7, s3, 0
	s_add_i32 s43, s41, 0x4000
	global_load_lds_dwordx4 v154, s[2:3]
	s_mov_b32 m0, s43
	s_add_i32 s44, s41, 0x6000
	global_load_lds_dwordx4 v158, s[6:7]
	s_mov_b32 m0, s44
	v_mov_b32_e32 v157, v145
	global_load_lds_dwordx4 v154, s[6:7]
	v_mov_b32_e32 v153, v145
	v_mov_b32_e32 v159, v145
	v_mov_b32_e32 v155, v145
	s_cmp_eq_u32 s8, 1
	v_lshl_add_u64 v[6:7], s[18:19], 0, v[156:157]
	v_lshl_add_u64 v[4:5], s[18:19], 0, v[152:153]
	v_lshl_add_u64 v[0:1], s[2:3], 0, v[158:159]
	s_cselect_b64 s[22:23], -1, 0
	s_cmp_lg_u32 s8, 1
	v_lshl_add_u64 v[2:3], s[2:3], 0, v[154:155]
	s_cbranch_scc1 .LBB0_775
	s_barrier

;     __device__ __forceinline__ void operator()(const f32x4 (&acc)[2][2][4][2], const Unit& u, int wr, int wc, int fr, int fq) const {
;         int seqbase, t0, slen; halo_decode(u.pm, seqbase, t0, slen);
;         const f32x4* ct = (const f32x4*)(CT + (size_t)(128 * u.pn) * 8) + (32 * wc + 8 * fq) * 2;
;         const bool f0 = (fr == 0), f15 = (fr == 15);
; #pragma unroll
;         for (int ai = 0; ai < 2; ++ai) {
;             const int tbase = t0 + 62 * (2 * ai + wr) - 1;
;             float rs[4];
; #pragma unroll
;             for (int m = 0; m < 4; ++m) { const int t = tbase + 16 * m + fr; const bool vin = (t >= 0) && (t < slen); const int grow = seqbase + (vin ? t : 0);
;                 const f32x4 p = *(const f32x4*)(PS + (size_t)grow * 16 + 4 * fq); float s = (p[0] + p[1]) + (p[2] + p[3]); s = bfly_add<16>(s); s = bfly_add<32>(s); rs[m] = vin ? rsqrtf(s * (1.f / DM) + EPS) : 0.f; }
.LBB0_790:
	s_cmpk_gt_i32 s36, 0x10f
	s_cbranch_scc1 EC2_smp
	s_mul_hi_i32 s86, s36, 0x78787879
	s_lshr_b32 s87, s86, 31
	s_ashr_i32 s86, s86, 4
	s_add_i32 s86, s86, s87
	s_lshl_b32 s88, s86, 13
	s_mul_i32 s86, s86, 34
	s_sub_i32 s86, s36, s86
	s_movk_i32 s91, 0x2000
	s_branch EC2_join
EC2_smp:
	s_add_i32 s86, s36, 0xfffffef0
	s_mul_hi_u32 s87, s86, 0x38e38e39
	s_lshr_b32 s87, s87, 1
	s_lshl_b32 s88, s87, 11
	s_add_i32 s88, s88, 0x10000
	s_mul_i32 s87, s87, 9
	s_sub_i32 s86, s86, s87
	s_movk_i32 s91, 0x800
EC2_join:
	s_mul_i32 s86, s86, 0xf8
	s_bfe_u32 s89, s81, 0x10008
	s_mul_i32 s89, s89, 62
	s_add_i32 s89, s89, s86
	s_add_i32 s89, s89, -1
	v_readlane_b32 s64, v254, 0
	v_readlane_b32 s65, v254, 1
	v_readlane_b32 s66, v255, 4
	s_nop 2
	s_load_dwordx2 s[98:99], s[64:65], 0xe0
	s_mul_i32 s66, s66, 0x16000
	s_bfe_u32 s32, s81, 0x20006
	s_movk_i32 s54, 0x1600
	v_mbcnt_lo_u32_b32 v176, -1, 0
	v_mbcnt_hi_u32_b32 v176, -1, v176
	v_and_b32_e32 v170, 15, v176
	v_lshlrev_b32_e32 v170, 2, v170
	v_bfe_u32 v171, v176, 4, 2
	v_lshlrev_b32_e32 v172, 8, v171
	v_lshlrev_b32_e32 v171, 4, v171
	v_mov_b32_e32 v252, s78
	s_waitcnt lgkmcnt(0)
	s_lshl_b32 s51, s33, 12
	s_add_i32 s51, s51, s66
	s_lshl_b32 s52, s32, 10
	s_add_i32 s51, s51, s52
	s_add_i32 s51, s51, 0x3500000
	s_add_u32 s100, s98, s51
	s_addc_u32 s101, s99, 0
	s_add_u32 s70, s98, 0x3600000
	s_addc_u32 s71, s99, 0
	s_lshl_b32 s51, s33, 8
	s_lshl_b32 s52, s32, 6
	s_add_i32 s51, s51, s52
	s_add_i32 s51, s51, 0xf400000
	s_add_u32 s86, s98, s51
	s_addc_u32 s87, s99, 0
	v_add_u32_e32 v174, s89, v170
	v_add_u32_e32 v176, 0, v174
	v_cmp_gt_u32_e64 s[52:53], s91, v176
	s_nop 1
	v_cndmask_b32_e64 v176, 0, v176, s[52:53]
	v_add_u32_e32 v176, s88, v176
	v_lshl_add_u32 v248, v176, 6, v171
	global_load_dwordx4 v[222:225], v248, s[70:71]
	v_add_u32_e32 v176, 1, v174
	v_cmp_gt_u32_e64 s[64:65], s91, v176
	s_nop 1
	v_cndmask_b32_e64 v176, 0, v176, s[64:65]
	v_add_u32_e32 v176, s88, v176
	v_lshl_add_u32 v249, v176, 6, v171
	global_load_dwordx4 v[226:229], v249, s[70:71]
	v_add_u32_e32 v176, 2, v174
	v_cmp_gt_u32_e64 s[98:99], s91, v176
	s_nop 1
	v_cndmask_b32_e64 v176, 0, v176, s[98:99]
	v_add_u32_e32 v176, s88, v176
	v_lshl_add_u32 v250, v176, 6, v171
	global_load_dwordx4 v[230:233], v250, s[70:71]
	v_add_u32_e32 v176, 3, v174
	v_cmp_gt_u32_e64 s[32:33], s91, v176
	s_nop 1
	v_cndmask_b32_e64 v176, 0, v176, s[32:33]
	v_add_u32_e32 v176, s88, v176
	v_lshl_add_u32 v251, v176, 6, v171
	global_load_dwordx4 v[234:237], v251, s[70:71]
	global_load_dwordx4 v[190:193], v172, s[100:101]
	global_load_dwordx4 v[194:197], v172, s[100:101] offset:16
	global_load_dwordx4 v[198:201], v172, s[100:101] offset:32
	global_load_dwordx4 v[202:205], v172, s[100:101] offset:48
	s_waitcnt vmcnt(7)
	v_add_f32_e32 v222, v222, v223
	v_add_f32_e32 v224, v224, v225
	v_add_f32_e32 v222, v222, v224
	v_mov_b32_e32 v223, v222
	s_nop 1
	v_permlane16_swap_b32_e32 v222, v223
	v_add_f32_e32 v222, v222, v223
	v_mov_b32_e32 v223, v222
	s_nop 1
	v_permlane32_swap_b32_e32 v222, v223
	v_add_f32_e32 v222, v222, v223
	v_fma_f32 v222, v222, s82, v252
	v_cmp_gt_f32_e32 vcc, s62, v222
	v_mul_f32_e32 v223, 0x4b800000, v222
	s_nop 0
	v_cndmask_b32_e32 v222, v222, v223, vcc
	v_rsq_f32_e32 v222, v222
	s_nop 0
	v_mul_f32_e32 v223, 0x45800000, v222
	v_cndmask_b32_e32 v222, v222, v223, vcc
	v_cndmask_b32_e64 v178, 0, v222, s[52:53]
	s_waitcnt vmcnt(6)
	v_add_f32_e32 v226, v226, v227
	v_add_f32_e32 v228, v228, v229
	v_add_f32_e32 v226, v226, v228
	v_mov_b32_e32 v227, v226
	s_nop 1
	v_permlane16_swap_b32_e32 v226, v227
	v_add_f32_e32 v226, v226, v227
	v_mov_b32_e32 v227, v226
	s_nop 1
	v_permlane32_swap_b32_e32 v226, v227
	v_add_f32_e32 v226, v226, v227
	v_fma_f32 v226, v226, s82, v252
	v_cmp_gt_f32_e32 vcc, s62, v226
	v_mul_f32_e32 v227, 0x4b800000, v226
	s_nop 0
	v_cndmask_b32_e32 v226, v226, v227, vcc
	v_rsq_f32_e32 v226, v226
	s_nop 0
	v_mul_f32_e32 v227, 0x45800000, v226
	v_cndmask_b32_e32 v226, v226, v227, vcc
	v_cndmask_b32_e64 v180, 0, v226, s[64:65]
	s_waitcnt vmcnt(5)
	v_add_f32_e32 v230, v230, v231
	v_add_f32_e32 v232, v232, v233
	v_add_f32_e32 v230, v230, v232
	v_mov_b32_e32 v231, v230
	s_nop 1
	v_permlane16_swap_b32_e32 v230, v231
	v_add_f32_e32 v230, v230, v231
	v_mov_b32_e32 v231, v230
	s_nop 1
	v_permlane32_swap_b32_e32 v230, v231
	v_add_f32_e32 v230, v230, v231
	v_fma_f32 v230, v230, s82, v252
	v_cmp_gt_f32_e32 vcc, s62, v230
	v_mul_f32_e32 v231, 0x4b800000, v230
	s_nop 0
	v_cndmask_b32_e32 v230, v230, v231, vcc
	v_rsq_f32_e32 v230, v230
	s_nop 0
	v_mul_f32_e32 v231, 0x45800000, v230
	v_cndmask_b32_e32 v230, v230, v231, vcc
	v_cndmask_b32_e64 v182, 0, v230, s[98:99]
	s_waitcnt vmcnt(4)
	v_add_f32_e32 v234, v234, v235
	v_add_f32_e32 v236, v236, v237
	v_add_f32_e32 v234, v234, v236
	v_mov_b32_e32 v235, v234
	s_nop 1
	v_permlane16_swap_b32_e32 v234, v235
	v_add_f32_e32 v234, v234, v235
	v_mov_b32_e32 v235, v234
	s_nop 1
	v_permlane32_swap_b32_e32 v234, v235
	v_add_f32_e32 v234, v234, v235
	v_fma_f32 v234, v234, s82, v252
	v_cmp_gt_f32_e32 vcc, s62, v234
	v_mul_f32_e32 v235, 0x4b800000, v234
	s_nop 0
	v_cndmask_b32_e32 v234, v234, v235, vcc
	v_rsq_f32_e32 v234, v234
	s_nop 0
	v_mul_f32_e32 v235, 0x45800000, v234
	v_cndmask_b32_e32 v234, v234, v235, vcc
	v_cndmask_b32_e64 v144, 0, v234, s[32:33]
	global_load_dwordx4 v[206:209], v172, s[100:101] offset:64
	global_load_dwordx4 v[210:213], v172, s[100:101] offset:80
	global_load_dwordx4 v[214:217], v172, s[100:101] offset:96
	global_load_dwordx4 v[218:221], v172, s[100:101] offset:112
	s_waitcnt vmcnt(4)
;     __device__ __forceinline__ void operator()(const f32x4 (&acc)[2][2][4][2], const Unit& u, int wr, int wc, int fr, int fq) const {
;     ...
;             for (int n = 0; n < 2; ++n)
; #pragma unroll
;                 for (int jp = 0; jp < 2; ++jp) {
;                     const int cidx = (4 * n + 2 * jp) * 2;
;                     const f32x4 c0a = ct[cidx], c0b = ct[cidx + 1], c1a = ct[cidx + 2], c1b = ct[cidx + 3];
;                     const f32x2 wv0 = {c0a[0], c1a[0]}, wv1 = {c0a[1], c1a[1]}, wv2 = {c0a[2], c1a[2]}, bv = {c0a[3], c1a[3]};
;                     const f32x2 wg0 = {c0b[0], c1b[0]}, wg1 = {c0b[1], c1b[1]}, wg2 = {c0b[2], c1b[2]}, bg = {c0b[3], c1b[3]};
;                     f32x2 uv[4], ug[4], cv[4];
; #pragma unroll
;                     for (int m = 0; m < 4; ++m) { uv[m] = (f32x2){acc[ai][0][m][n][2 * jp], acc[ai][0][m][n][2 * jp + 1]}; ug[m] = (f32x2){acc[ai][1][m][n][2 * jp], acc[ai][1][m][n][2 * jp + 1]}; }
;                     asm volatile("" : "+v"(uv[0]), "+v"(uv[1]), "+v"(uv[2]), "+v"(uv[3]), "+v"(ug[0]), "+v"(ug[1]), "+v"(ug[2]), "+v"(ug[3]));
;                     {
;                         f32x2 rv[4], lv[4];
; #pragma unroll
;                         for (int m = 0; m < 4; ++m) { uv[m] = uv[m] * rs[m]; rv[m] = (f32x2){dpp_ror1(uv[m][0]), dpp_ror1(uv[m][1])}; lv[m] = (f32x2){dpp_ror15(uv[m][0]), dpp_ror15(uv[m][1])}; }
; #pragma unroll
;                         for (int m = 0; m < 4; ++m) { const f32x2 pv_ = (m > 0 && f0) ? rv[m > 0 ? m - 1 : 0] : rv[m], nv_ = (m < 3 && f15) ? lv[m < 3 ? m + 1 : 3] : lv[m];
;                             cv[m] = bv + wv0 * pv_ + wv1 * uv[m] + wv2 * nv_; }
;                     }
;                     asm volatile("" : "+v"(cv[0]), "+v"(cv[1]), "+v"(cv[2]), "+v"(cv[3]));
;                     {
;                         f32x2 rg[4], lg[4];
; #pragma unroll
;                         for (int m = 0; m < 4; ++m) { ug[m] = ug[m] * rs[m]; rg[m] = (f32x2){dpp_ror1(ug[m][0]), dpp_ror1(ug[m][1])}; lg[m] = (f32x2){dpp_ror15(ug[m][0]), dpp_ror15(ug[m][1])}; }
; #pragma unroll
;                         for (int m = 0; m < 4; ++m) { const f32x2 pg_ = (m > 0 && f0) ? rg[m > 0 ? m - 1 : 0] : rg[m], ng_ = (m < 3 && f15) ? lg[m < 3 ? m + 1 : 3] : lg[m];
;                             const f32x2 cgt = bg + wg0 * pg_ + wg1 * ug[m] + wg2 * ng_;
;                             const f32x2 e = cgt * (-LOG2E);
	v_pk_mul_f32 v[124:125], v[124:125], v[178:179] op_sel_hi:[1,0]
	v_pk_mul_f32 v[120:121], v[120:121], v[180:181] op_sel_hi:[1,0]
	v_pk_mul_f32 v[116:117], v[116:117], v[182:183] op_sel_hi:[1,0]
	v_pk_mul_f32 v[112:113], v[112:113], v[144:145] op_sel_hi:[1,0]
	v_pk_mul_f32 v[108:109], v[108:109], v[178:179] op_sel_hi:[1,0]
	v_pk_mul_f32 v[104:105], v[104:105], v[180:181] op_sel_hi:[1,0]
	v_pk_mul_f32 v[100:101], v[100:101], v[182:183] op_sel_hi:[1,0]
	v_pk_mul_f32 v[96:97], v[96:97], v[144:145] op_sel_hi:[1,0]
	s_nop 1
	v_mov_b32_dpp v248, v112 row_shr:1 row_mask:0xf bank_mask:0xf bound_ctrl:1
	v_mov_b32_dpp v249, v113 row_shr:1 row_mask:0xf bank_mask:0xf bound_ctrl:1
	v_mov_b32_dpp v250, v124 row_shl:1 row_mask:0xf bank_mask:0xf bound_ctrl:1
	v_mov_b32_dpp v251, v125 row_shl:1 row_mask:0xf bank_mask:0xf bound_ctrl:1
	v_pk_fma_f32 v[224:225], v[190:191], v[248:249], v[196:197]
	v_pk_fma_f32 v[226:227], v[190:191], v[124:125], v[196:197]
	v_pk_fma_f32 v[228:229], v[190:191], v[120:121], v[196:197]
	v_pk_fma_f32 v[230:231], v[190:191], v[116:117], v[196:197]
	v_pk_fma_f32 v[224:225], v[192:193], v[124:125], v[224:225]
	v_pk_fma_f32 v[226:227], v[192:193], v[120:121], v[226:227]
	v_pk_fma_f32 v[228:229], v[192:193], v[116:117], v[228:229]
	v_pk_fma_f32 v[230:231], v[192:193], v[112:113], v[230:231]
	v_pk_fma_f32 v[224:225], v[194:195], v[120:121], v[224:225]
	v_pk_fma_f32 v[226:227], v[194:195], v[116:117], v[226:227]
	v_pk_fma_f32 v[228:229], v[194:195], v[112:113], v[228:229]
	v_pk_fma_f32 v[230:231], v[194:195], v[250:251], v[230:231]
	s_nop 1
	v_mov_b32_dpp v248, v96 row_shr:1 row_mask:0xf bank_mask:0xf bound_ctrl:1
	v_mov_b32_dpp v249, v97 row_shr:1 row_mask:0xf bank_mask:0xf bound_ctrl:1
	v_mov_b32_dpp v250, v108 row_shl:1 row_mask:0xf bank_mask:0xf bound_ctrl:1
	v_mov_b32_dpp v251, v109 row_shl:1 row_mask:0xf bank_mask:0xf bound_ctrl:1
	v_pk_fma_f32 v[232:233], v[198:199], v[248:249], v[204:205]
	v_pk_fma_f32 v[234:235], v[198:199], v[108:109], v[204:205]
	v_pk_fma_f32 v[236:237], v[198:199], v[104:105], v[204:205]
	v_pk_fma_f32 v[238:239], v[198:199], v[100:101], v[204:205]
	v_pk_fma_f32 v[232:233], v[200:201], v[108:109], v[232:233]
	v_pk_fma_f32 v[234:235], v[200:201], v[104:105], v[234:235]
	v_pk_fma_f32 v[236:237], v[200:201], v[100:101], v[236:237]
	v_pk_fma_f32 v[238:239], v[200:201], v[96:97], v[238:239]
	v_pk_fma_f32 v[232:233], v[202:203], v[104:105], v[232:233]
	v_pk_fma_f32 v[234:235], v[202:203], v[100:101], v[234:235]
	v_pk_fma_f32 v[236:237], v[202:203], v[96:97], v[236:237]
	v_pk_fma_f32 v[238:239], v[202:203], v[250:251], v[238:239]
	v_exp_f32_e64 v240, -v232
	v_exp_f32_e64 v241, -v233
	v_exp_f32_e64 v242, -v234
	v_exp_f32_e64 v243, -v235
	v_exp_f32_e64 v244, -v236
	v_exp_f32_e64 v245, -v237
	v_exp_f32_e64 v246, -v238
	v_exp_f32_e64 v247, -v239
	v_pk_mul_f32 v[224:225], v[224:225], v[232:233]
	v_pk_mul_f32 v[226:227], v[226:227], v[234:235]
	v_pk_mul_f32 v[228:229], v[228:229], v[236:237]
	v_pk_mul_f32 v[230:231], v[230:231], v[238:239]
	v_pk_add_f32 v[240:241], v[240:241], 1.0 op_sel_hi:[1,0]
	v_pk_add_f32 v[242:243], v[242:243], 1.0 op_sel_hi:[1,0]
	v_pk_add_f32 v[244:245], v[244:245], 1.0 op_sel_hi:[1,0]
	v_pk_add_f32 v[246:247], v[246:247], 1.0 op_sel_hi:[1,0]
	v_rcp_f32_e32 v240, v240
	v_rcp_f32_e32 v241, v241
	v_rcp_f32_e32 v242, v242
	v_rcp_f32_e32 v243, v243
	v_rcp_f32_e32 v244, v244
	v_rcp_f32_e32 v245, v245
	v_rcp_f32_e32 v246, v246
	v_rcp_f32_e32 v247, v247
	s_nop 0
	v_pk_mul_f32 v[224:225], v[224:225], v[240:241]
	v_pk_mul_f32 v[226:227], v[226:227], v[242:243]
	v_pk_mul_f32 v[228:229], v[228:229], v[244:245]
	v_pk_mul_f32 v[230:231], v[230:231], v[246:247]
	v_cvt_pk_bf16_f32 v128, v224, v225
	v_cvt_pk_bf16_f32 v132, v226, v227
	v_cvt_pk_bf16_f32 v136, v228, v229
	v_cvt_pk_bf16_f32 v140, v230, v231
	global_load_dwordx4 v[190:193], v172, s[100:101] offset:128
	global_load_dwordx4 v[194:197], v172, s[100:101] offset:144
	global_load_dwordx4 v[198:201], v172, s[100:101] offset:160
	global_load_dwordx4 v[202:205], v172, s[100:101] offset:176
	s_waitcnt vmcnt(4)
	v_pk_mul_f32 v[126:127], v[126:127], v[178:179] op_sel_hi:[1,0]
	v_pk_mul_f32 v[122:123], v[122:123], v[180:181] op_sel_hi:[1,0]
	v_pk_mul_f32 v[118:119], v[118:119], v[182:183] op_sel_hi:[1,0]
	v_pk_mul_f32 v[114:115], v[114:115], v[144:145] op_sel_hi:[1,0]
	v_pk_mul_f32 v[110:111], v[110:111], v[178:179] op_sel_hi:[1,0]
	v_pk_mul_f32 v[106:107], v[106:107], v[180:181] op_sel_hi:[1,0]
	v_pk_mul_f32 v[102:103], v[102:103], v[182:183] op_sel_hi:[1,0]
	v_pk_mul_f32 v[98:99], v[98:99], v[144:145] op_sel_hi:[1,0]
	s_nop 1
	v_mov_b32_dpp v248, v114 row_shr:1 row_mask:0xf bank_mask:0xf bound_ctrl:1
	v_mov_b32_dpp v249, v115 row_shr:1 row_mask:0xf bank_mask:0xf bound_ctrl:1
	v_mov_b32_dpp v250, v126 row_shl:1 row_mask:0xf bank_mask:0xf bound_ctrl:1
	v_mov_b32_dpp v251, v127 row_shl:1 row_mask:0xf bank_mask:0xf bound_ctrl:1
	v_pk_fma_f32 v[224:225], v[206:207], v[248:249], v[212:213]
	v_pk_fma_f32 v[226:227], v[206:207], v[126:127], v[212:213]
	v_pk_fma_f32 v[228:229], v[206:207], v[122:123], v[212:213]
	v_pk_fma_f32 v[230:231], v[206:207], v[118:119], v[212:213]
	v_pk_fma_f32 v[224:225], v[208:209], v[126:127], v[224:225]
	v_pk_fma_f32 v[226:227], v[208:209], v[122:123], v[226:227]
	v_pk_fma_f32 v[228:229], v[208:209], v[118:119], v[228:229]
	v_pk_fma_f32 v[230:231], v[208:209], v[114:115], v[230:231]
	v_pk_fma_f32 v[224:225], v[210:211], v[122:123], v[224:225]
	v_pk_fma_f32 v[226:227], v[210:211], v[118:119], v[226:227]
	v_pk_fma_f32 v[228:229], v[210:211], v[114:115], v[228:229]
	v_pk_fma_f32 v[230:231], v[210:211], v[250:251], v[230:231]
	s_nop 1
;     __device__ __forceinline__ void operator()(const f32x4 (&acc)[2][2][4][2], const Unit& u, int wr, int wc, int fr, int fq) const {
;     ...
;             for (int n = 0; n < 2; ++n)
; #pragma unroll
;                 for (int jp = 0; jp < 2; ++jp) {
;                     const int cidx = (4 * n + 2 * jp) * 2;
;                     const f32x4 c0a = ct[cidx], c0b = ct[cidx + 1], c1a = ct[cidx + 2], c1b = ct[cidx + 3];
;                     const f32x2 wv0 = {c0a[0], c1a[0]}, wv1 = {c0a[1], c1a[1]}, wv2 = {c0a[2], c1a[2]}, bv = {c0a[3], c1a[3]};
;                     const f32x2 wg0 = {c0b[0], c1b[0]}, wg1 = {c0b[1], c1b[1]}, wg2 = {c0b[2], c1b[2]}, bg = {c0b[3], c1b[3]};
;                     f32x2 uv[4], ug[4], cv[4];
; #pragma unroll
;                     for (int m = 0; m < 4; ++m) { uv[m] = (f32x2){acc[ai][0][m][n][2 * jp], acc[ai][0][m][n][2 * jp + 1]}; ug[m] = (f32x2){acc[ai][1][m][n][2 * jp], acc[ai][1][m][n][2 * jp + 1]}; }
;                     asm volatile("" : "+v"(uv[0]), "+v"(uv[1]), "+v"(uv[2]), "+v"(uv[3]), "+v"(ug[0]), "+v"(ug[1]), "+v"(ug[2]), "+v"(ug[3]));
;                     {
;                         f32x2 rv[4], lv[4];
; #pragma unroll
;                         for (int m = 0; m < 4; ++m) { uv[m] = uv[m] * rs[m]; rv[m] = (f32x2){dpp_ror1(uv[m][0]), dpp_ror1(uv[m][1])}; lv[m] = (f32x2){dpp_ror15(uv[m][0]), dpp_ror15(uv[m][1])}; }
; #pragma unroll
;                         for (int m = 0; m < 4; ++m) { const f32x2 pv_ = (m > 0 && f0) ? rv[m > 0 ? m - 1 : 0] : rv[m], nv_ = (m < 3 && f15) ? lv[m < 3 ? m + 1 : 3] : lv[m];
;                             cv[m] = bv + wv0 * pv_ + wv1 * uv[m] + wv2 * nv_; }
;                     }
;                     asm volatile("" : "+v"(cv[0]), "+v"(cv[1]), "+v"(cv[2]), "+v"(cv[3]));
;                     {
;                         f32x2 rg[4], lg[4];
; #pragma unroll
;                         for (int m = 0; m < 4; ++m) { ug[m] = ug[m] * rs[m]; rg[m] = (f32x2){dpp_ror1(ug[m][0]), dpp_ror1(ug[m][1])}; lg[m] = (f32x2){dpp_ror15(ug[m][0]), dpp_ror15(ug[m][1])}; }
; #pragma unroll
;                         for (int m = 0; m < 4; ++m) { const f32x2 pg_ = (m > 0 && f0) ? rg[m > 0 ? m - 1 : 0] : rg[m], ng_ = (m < 3 && f15) ? lg[m < 3 ? m + 1 : 3] : lg[m];
;                             const f32x2 cgt = bg + wg0 * pg_ + wg1 * ug[m] + wg2 * ng_;
;                             const f32x2 e = cgt * (-LOG2E);
	v_mov_b32_dpp v248, v98 row_shr:1 row_mask:0xf bank_mask:0xf bound_ctrl:1
	v_mov_b32_dpp v249, v99 row_shr:1 row_mask:0xf bank_mask:0xf bound_ctrl:1
	v_mov_b32_dpp v250, v110 row_shl:1 row_mask:0xf bank_mask:0xf bound_ctrl:1
	v_mov_b32_dpp v251, v111 row_shl:1 row_mask:0xf bank_mask:0xf bound_ctrl:1
	v_pk_fma_f32 v[232:233], v[214:215], v[248:249], v[220:221]
	v_pk_fma_f32 v[234:235], v[214:215], v[110:111], v[220:221]
	v_pk_fma_f32 v[236:237], v[214:215], v[106:107], v[220:221]
	v_pk_fma_f32 v[238:239], v[214:215], v[102:103], v[220:221]
	v_pk_fma_f32 v[232:233], v[216:217], v[110:111], v[232:233]
	v_pk_fma_f32 v[234:235], v[216:217], v[106:107], v[234:235]
	v_pk_fma_f32 v[236:237], v[216:217], v[102:103], v[236:237]
	v_pk_fma_f32 v[238:239], v[216:217], v[98:99], v[238:239]
	v_pk_fma_f32 v[232:233], v[218:219], v[106:107], v[232:233]
	v_pk_fma_f32 v[234:235], v[218:219], v[102:103], v[234:235]
	v_pk_fma_f32 v[236:237], v[218:219], v[98:99], v[236:237]
	v_pk_fma_f32 v[238:239], v[218:219], v[250:251], v[238:239]
	v_exp_f32_e64 v240, -v232
	v_exp_f32_e64 v241, -v233
	v_exp_f32_e64 v242, -v234
	v_exp_f32_e64 v243, -v235
	v_exp_f32_e64 v244, -v236
	v_exp_f32_e64 v245, -v237
	v_exp_f32_e64 v246, -v238
	v_exp_f32_e64 v247, -v239
	v_pk_mul_f32 v[224:225], v[224:225], v[232:233]
	v_pk_mul_f32 v[226:227], v[226:227], v[234:235]
	v_pk_mul_f32 v[228:229], v[228:229], v[236:237]
	v_pk_mul_f32 v[230:231], v[230:231], v[238:239]
	v_pk_add_f32 v[240:241], v[240:241], 1.0 op_sel_hi:[1,0]
	v_pk_add_f32 v[242:243], v[242:243], 1.0 op_sel_hi:[1,0]
	v_pk_add_f32 v[244:245], v[244:245], 1.0 op_sel_hi:[1,0]
	v_pk_add_f32 v[246:247], v[246:247], 1.0 op_sel_hi:[1,0]
	v_rcp_f32_e32 v240, v240
	v_rcp_f32_e32 v241, v241
	v_rcp_f32_e32 v242, v242
	v_rcp_f32_e32 v243, v243
	v_rcp_f32_e32 v244, v244
	v_rcp_f32_e32 v245, v245
	v_rcp_f32_e32 v246, v246
	v_rcp_f32_e32 v247, v247
	s_nop 0
	v_pk_mul_f32 v[224:225], v[224:225], v[240:241]
	v_pk_mul_f32 v[226:227], v[226:227], v[242:243]
	v_pk_mul_f32 v[228:229], v[228:229], v[244:245]
	v_pk_mul_f32 v[230:231], v[230:231], v[246:247]
	v_cvt_pk_bf16_f32 v129, v224, v225
	v_cvt_pk_bf16_f32 v133, v226, v227
	v_cvt_pk_bf16_f32 v137, v228, v229
	v_cvt_pk_bf16_f32 v141, v230, v231
	global_load_dwordx4 v[206:209], v172, s[100:101] offset:192
	global_load_dwordx4 v[210:213], v172, s[100:101] offset:208
	global_load_dwordx4 v[214:217], v172, s[100:101] offset:224
	global_load_dwordx4 v[218:221], v172, s[100:101] offset:240
	s_waitcnt vmcnt(4)
	v_pk_mul_f32 v[92:93], v[92:93], v[178:179] op_sel_hi:[1,0]
	v_pk_mul_f32 v[88:89], v[88:89], v[180:181] op_sel_hi:[1,0]
	v_pk_mul_f32 v[84:85], v[84:85], v[182:183] op_sel_hi:[1,0]
	v_pk_mul_f32 v[80:81], v[80:81], v[144:145] op_sel_hi:[1,0]
	v_pk_mul_f32 v[76:77], v[76:77], v[178:179] op_sel_hi:[1,0]
	v_pk_mul_f32 v[72:73], v[72:73], v[180:181] op_sel_hi:[1,0]
	v_pk_mul_f32 v[68:69], v[68:69], v[182:183] op_sel_hi:[1,0]
	v_pk_mul_f32 v[64:65], v[64:65], v[144:145] op_sel_hi:[1,0]
	s_nop 1
	v_mov_b32_dpp v248, v80 row_shr:1 row_mask:0xf bank_mask:0xf bound_ctrl:1
	v_mov_b32_dpp v249, v81 row_shr:1 row_mask:0xf bank_mask:0xf bound_ctrl:1
	v_mov_b32_dpp v250, v92 row_shl:1 row_mask:0xf bank_mask:0xf bound_ctrl:1
	v_mov_b32_dpp v251, v93 row_shl:1 row_mask:0xf bank_mask:0xf bound_ctrl:1
	v_pk_fma_f32 v[224:225], v[190:191], v[248:249], v[196:197]
	v_pk_fma_f32 v[226:227], v[190:191], v[92:93], v[196:197]
	v_pk_fma_f32 v[228:229], v[190:191], v[88:89], v[196:197]
	v_pk_fma_f32 v[230:231], v[190:191], v[84:85], v[196:197]
	v_pk_fma_f32 v[224:225], v[192:193], v[92:93], v[224:225]
	v_pk_fma_f32 v[226:227], v[192:193], v[88:89], v[226:227]
	v_pk_fma_f32 v[228:229], v[192:193], v[84:85], v[228:229]
	v_pk_fma_f32 v[230:231], v[192:193], v[80:81], v[230:231]
	v_pk_fma_f32 v[224:225], v[194:195], v[88:89], v[224:225]
	v_pk_fma_f32 v[226:227], v[194:195], v[84:85], v[226:227]
	v_pk_fma_f32 v[228:229], v[194:195], v[80:81], v[228:229]
	v_pk_fma_f32 v[230:231], v[194:195], v[250:251], v[230:231]
	s_nop 1
	v_mov_b32_dpp v248, v64 row_shr:1 row_mask:0xf bank_mask:0xf bound_ctrl:1
	v_mov_b32_dpp v249, v65 row_shr:1 row_mask:0xf bank_mask:0xf bound_ctrl:1
	v_mov_b32_dpp v250, v76 row_shl:1 row_mask:0xf bank_mask:0xf bound_ctrl:1
	v_mov_b32_dpp v251, v77 row_shl:1 row_mask:0xf bank_mask:0xf bound_ctrl:1
	v_pk_fma_f32 v[232:233], v[198:199], v[248:249], v[204:205]
	v_pk_fma_f32 v[234:235], v[198:199], v[76:77], v[204:205]
	v_pk_fma_f32 v[236:237], v[198:199], v[72:73], v[204:205]
	v_pk_fma_f32 v[238:239], v[198:199], v[68:69], v[204:205]
	v_pk_fma_f32 v[232:233], v[200:201], v[76:77], v[232:233]
	v_pk_fma_f32 v[234:235], v[200:201], v[72:73], v[234:235]
	v_pk_fma_f32 v[236:237], v[200:201], v[68:69], v[236:237]
	v_pk_fma_f32 v[238:239], v[200:201], v[64:65], v[238:239]
	v_pk_fma_f32 v[232:233], v[202:203], v[72:73], v[232:233]
	v_pk_fma_f32 v[234:235], v[202:203], v[68:69], v[234:235]
	v_pk_fma_f32 v[236:237], v[202:203], v[64:65], v[236:237]
	v_pk_fma_f32 v[238:239], v[202:203], v[250:251], v[238:239]
	v_exp_f32_e64 v240, -v232
	v_exp_f32_e64 v241, -v233
	v_exp_f32_e64 v242, -v234
	v_exp_f32_e64 v243, -v235
	v_exp_f32_e64 v244, -v236
	v_exp_f32_e64 v245, -v237
	v_exp_f32_e64 v246, -v238
	v_exp_f32_e64 v247, -v239
	v_pk_mul_f32 v[224:225], v[224:225], v[232:233]
	v_pk_mul_f32 v[226:227], v[226:227], v[234:235]
	v_pk_mul_f32 v[228:229], v[228:229], v[236:237]
	v_pk_mul_f32 v[230:231], v[230:231], v[238:239]
	v_pk_add_f32 v[240:241], v[240:241], 1.0 op_sel_hi:[1,0]
	v_pk_add_f32 v[242:243], v[242:243], 1.0 op_sel_hi:[1,0]
	v_pk_add_f32 v[244:245], v[244:245], 1.0 op_sel_hi:[1,0]
	v_pk_add_f32 v[246:247], v[246:247], 1.0 op_sel_hi:[1,0]
	v_rcp_f32_e32 v240, v240
	v_rcp_f32_e32 v241, v241
	v_rcp_f32_e32 v242, v242
	v_rcp_f32_e32 v243, v243
	v_rcp_f32_e32 v244, v244
	v_rcp_f32_e32 v245, v245
	v_rcp_f32_e32 v246, v246
	v_rcp_f32_e32 v247, v247
	s_nop 0
	v_pk_mul_f32 v[224:225], v[224:225], v[240:241]
	v_pk_mul_f32 v[226:227], v[226:227], v[242:243]
	v_pk_mul_f32 v[228:229], v[228:229], v[244:245]
	v_pk_mul_f32 v[230:231], v[230:231], v[246:247]
	v_cvt_pk_bf16_f32 v130, v224, v225
	v_cvt_pk_bf16_f32 v134, v226, v227
	v_cvt_pk_bf16_f32 v138, v228, v229
	v_cvt_pk_bf16_f32 v142, v230, v231
	s_waitcnt vmcnt(0)
; __device__ __forceinline__ unsigned cvtpk(float lo, float hi) { f32x2 v = {lo, hi}; bf16x2_t b = __builtin_convertvector(v, bf16x2_t); return __builtin_bit_cast(unsigned, b); }
;     __device__ __forceinline__ void operator()(const f32x4 (&acc)[2][2][4][2], const Unit& u, int wr, int wc, int fr, int fq) const {
;     ...
;             const int tbase = t0 + 62 * (2 * ai + wr) - 1;
;             float rs[4];
; #pragma unroll
;             for (int m = 0; m < 4; ++m) { const int t = tbase + 16 * m + fr; const bool vin = (t >= 0) && (t < slen); const int grow = seqbase + (vin ? t : 0);
;                 const f32x4 p = *(const f32x4*)(PS + (size_t)grow * 16 + 4 * fq); float s = (p[0] + p[1]) + (p[2] + p[3]); s = bfly_add<16>(s); s = bfly_add<32>(s); rs[m] = vin ? rsqrtf(s * (1.f / DM) + EPS) : 0.f; }
;     ...
;                         for (int m = 0; m < 4; ++m) { ug[m] = ug[m] * rs[m]; rg[m] = (f32x2){dpp_ror1(ug[m][0]), dpp_ror1(ug[m][1])}; lg[m] = (f32x2){dpp_ror15(ug[m][0]), dpp_ror15(ug[m][1])}; }
; #pragma unroll
;                         for (int m = 0; m < 4; ++m) { const f32x2 pg_ = (m > 0 && f0) ? rg[m > 0 ? m - 1 : 0] : rg[m], ng_ = (m < 3 && f15) ? lg[m < 3 ? m + 1 : 3] : lg[m];
;                             const f32x2 cgt = bg + wg0 * pg_ + wg1 * ug[m] + wg2 * ng_;
;                             const f32x2 e = cgt * (-LOG2E);
;                             const f32x2 d = (f32x2){__builtin_amdgcn_exp2f(e[0]), __builtin_amdgcn_exp2f(e[1])} + 1.f;
;                             const f32x2 sg = {__builtin_amdgcn_rcpf(d[0]), __builtin_amdgcn_rcpf(d[1])};
;                             const f32x2 ov = cv[m] * cgt * sg;
;                             outw[m][n][jp] = cvtpk(ov[0], ov[1]); }
;                     }
;                     asm volatile("" : "+v"(outw[0][n][jp]), "+v"(outw[1][n][jp]), "+v"(outw[2][n][jp]), "+v"(outw[3][n][jp]) :: "memory"); __builtin_amdgcn_sched_barrier(0);
;                 }
; #pragma unroll
;             for (int m = 0; m < 4; ++m) { const int i = 16 * m + fr, t = tbase + i;
;                 if (i >= 1 && i <= 62 && t < slen) { u32x4 w; w.x = outw[m][0][0]; w.y = outw[m][0][1]; w.z = outw[m][1][0]; w.w = outw[m][1][1];
;                     *(u32x4*)(Gout + (size_t)(seqbase + t) * DFF + 128 * u.pn + 32 * wc + 8 * fq) = w; } }
	v_pk_mul_f32 v[94:95], v[94:95], v[178:179] op_sel_hi:[1,0]
	v_pk_mul_f32 v[90:91], v[90:91], v[180:181] op_sel_hi:[1,0]
	v_pk_mul_f32 v[86:87], v[86:87], v[182:183] op_sel_hi:[1,0]
	v_pk_mul_f32 v[82:83], v[82:83], v[144:145] op_sel_hi:[1,0]
	v_pk_mul_f32 v[78:79], v[78:79], v[178:179] op_sel_hi:[1,0]
	v_pk_mul_f32 v[74:75], v[74:75], v[180:181] op_sel_hi:[1,0]
	v_pk_mul_f32 v[70:71], v[70:71], v[182:183] op_sel_hi:[1,0]
	v_pk_mul_f32 v[66:67], v[66:67], v[144:145] op_sel_hi:[1,0]
	s_nop 1
	v_mov_b32_dpp v248, v82 row_shr:1 row_mask:0xf bank_mask:0xf bound_ctrl:1
	v_mov_b32_dpp v249, v83 row_shr:1 row_mask:0xf bank_mask:0xf bound_ctrl:1
	v_mov_b32_dpp v250, v94 row_shl:1 row_mask:0xf bank_mask:0xf bound_ctrl:1
	v_mov_b32_dpp v251, v95 row_shl:1 row_mask:0xf bank_mask:0xf bound_ctrl:1
	v_pk_fma_f32 v[224:225], v[206:207], v[248:249], v[212:213]
	v_pk_fma_f32 v[226:227], v[206:207], v[94:95], v[212:213]
	v_pk_fma_f32 v[228:229], v[206:207], v[90:91], v[212:213]
	v_pk_fma_f32 v[230:231], v[206:207], v[86:87], v[212:213]
	v_pk_fma_f32 v[224:225], v[208:209], v[94:95], v[224:225]
	v_pk_fma_f32 v[226:227], v[208:209], v[90:91], v[226:227]
	v_pk_fma_f32 v[228:229], v[208:209], v[86:87], v[228:229]
	v_pk_fma_f32 v[230:231], v[208:209], v[82:83], v[230:231]
	v_pk_fma_f32 v[224:225], v[210:211], v[90:91], v[224:225]
	v_pk_fma_f32 v[226:227], v[210:211], v[86:87], v[226:227]
	v_pk_fma_f32 v[228:229], v[210:211], v[82:83], v[228:229]
	v_pk_fma_f32 v[230:231], v[210:211], v[250:251], v[230:231]
	s_nop 1
	v_mov_b32_dpp v248, v66 row_shr:1 row_mask:0xf bank_mask:0xf bound_ctrl:1
	v_mov_b32_dpp v249, v67 row_shr:1 row_mask:0xf bank_mask:0xf bound_ctrl:1
	v_mov_b32_dpp v250, v78 row_shl:1 row_mask:0xf bank_mask:0xf bound_ctrl:1
	v_mov_b32_dpp v251, v79 row_shl:1 row_mask:0xf bank_mask:0xf bound_ctrl:1
	v_pk_fma_f32 v[232:233], v[214:215], v[248:249], v[220:221]
	v_pk_fma_f32 v[234:235], v[214:215], v[78:79], v[220:221]
	v_pk_fma_f32 v[236:237], v[214:215], v[74:75], v[220:221]
	v_pk_fma_f32 v[238:239], v[214:215], v[70:71], v[220:221]
	v_pk_fma_f32 v[232:233], v[216:217], v[78:79], v[232:233]
	v_pk_fma_f32 v[234:235], v[216:217], v[74:75], v[234:235]
	v_pk_fma_f32 v[236:237], v[216:217], v[70:71], v[236:237]
	v_pk_fma_f32 v[238:239], v[216:217], v[66:67], v[238:239]
	v_pk_fma_f32 v[232:233], v[218:219], v[74:75], v[232:233]
	v_pk_fma_f32 v[234:235], v[218:219], v[70:71], v[234:235]
	v_pk_fma_f32 v[236:237], v[218:219], v[66:67], v[236:237]
	v_pk_fma_f32 v[238:239], v[218:219], v[250:251], v[238:239]
	v_exp_f32_e64 v240, -v232
	v_exp_f32_e64 v241, -v233
	v_exp_f32_e64 v242, -v234
	v_exp_f32_e64 v243, -v235
	v_exp_f32_e64 v244, -v236
	v_exp_f32_e64 v245, -v237
	v_exp_f32_e64 v246, -v238
	v_exp_f32_e64 v247, -v239
	v_pk_mul_f32 v[224:225], v[224:225], v[232:233]
	v_pk_mul_f32 v[226:227], v[226:227], v[234:235]
	v_pk_mul_f32 v[228:229], v[228:229], v[236:237]
	v_pk_mul_f32 v[230:231], v[230:231], v[238:239]
	v_pk_add_f32 v[240:241], v[240:241], 1.0 op_sel_hi:[1,0]
	v_pk_add_f32 v[242:243], v[242:243], 1.0 op_sel_hi:[1,0]
	v_pk_add_f32 v[244:245], v[244:245], 1.0 op_sel_hi:[1,0]
	v_pk_add_f32 v[246:247], v[246:247], 1.0 op_sel_hi:[1,0]
	v_rcp_f32_e32 v240, v240
	v_rcp_f32_e32 v241, v241
	v_rcp_f32_e32 v242, v242
	v_rcp_f32_e32 v243, v243
	v_rcp_f32_e32 v244, v244
	v_rcp_f32_e32 v245, v245
	v_rcp_f32_e32 v246, v246
	v_rcp_f32_e32 v247, v247
	s_nop 0
	v_pk_mul_f32 v[224:225], v[224:225], v[240:241]
	v_pk_mul_f32 v[226:227], v[226:227], v[242:243]
	v_pk_mul_f32 v[228:229], v[228:229], v[244:245]
	v_pk_mul_f32 v[230:231], v[230:231], v[246:247]
	v_cvt_pk_bf16_f32 v131, v224, v225
	v_cvt_pk_bf16_f32 v135, v226, v227
	v_cvt_pk_bf16_f32 v139, v228, v229
	v_cvt_pk_bf16_f32 v143, v230, v231
	v_add_u32_e32 v176, 0, v174
	v_cmp_gt_u32_e32 vcc, s91, v176
	v_cmp_ne_u32_e64 s[52:53], 0, v170
	s_and_b64 vcc, vcc, s[52:53]
	v_add_u32_e32 v176, s88, v176
	v_mad_u32_u24 v248, v176, s54, v171
	s_and_saveexec_b64 s[64:65], vcc
	global_store_dwordx4 v248, v[128:131], s[86:87]
	s_mov_b64 exec, s[64:65]
	v_add_u32_e32 v176, 1, v174
	v_cmp_gt_u32_e32 vcc, s91, v176
	v_add_u32_e32 v176, s88, v176
	v_mad_u32_u24 v249, v176, s54, v171
	s_and_saveexec_b64 s[64:65], vcc
	global_store_dwordx4 v249, v[132:135], s[86:87]
	s_mov_b64 exec, s[64:65]
	v_add_u32_e32 v176, 2, v174
	v_cmp_gt_u32_e32 vcc, s91, v176
	v_add_u32_e32 v176, s88, v176
	v_mad_u32_u24 v250, v176, s54, v171
	s_and_saveexec_b64 s[64:65], vcc
	global_store_dwordx4 v250, v[136:139], s[86:87]
	s_mov_b64 exec, s[64:65]
	v_add_u32_e32 v176, 3, v174
	v_cmp_gt_u32_e32 vcc, s91, v176
	v_cmp_ne_u32_e64 s[52:53], 60, v170
	s_and_b64 vcc, vcc, s[52:53]
	v_add_u32_e32 v176, s88, v176
	v_mad_u32_u24 v251, v176, s54, v171
	s_and_saveexec_b64 s[64:65], vcc
	global_store_dwordx4 v251, v[140:143], s[86:87]
	s_mov_b64 exec, s[64:65]
	s_addk_i32 s89, 0x7c
	v_add_u32_e32 v174, s89, v170
	v_add_u32_e32 v176, 0, v174
	v_cmp_gt_u32_e64 s[52:53], s91, v176
	s_nop 1
	v_cndmask_b32_e64 v176, 0, v176, s[52:53]
	v_add_u32_e32 v176, s88, v176
	v_lshl_add_u32 v248, v176, 6, v171
	global_load_dwordx4 v[222:225], v248, s[70:71]
	v_add_u32_e32 v176, 1, v174
	v_cmp_gt_u32_e64 s[64:65], s91, v176
	s_nop 1
	v_cndmask_b32_e64 v176, 0, v176, s[64:65]
	v_add_u32_e32 v176, s88, v176
	v_lshl_add_u32 v249, v176, 6, v171
	global_load_dwordx4 v[226:229], v249, s[70:71]
	v_add_u32_e32 v176, 2, v174
	v_cmp_gt_u32_e64 s[98:99], s91, v176
	s_nop 1
	v_cndmask_b32_e64 v176, 0, v176, s[98:99]
	v_add_u32_e32 v176, s88, v176
	v_lshl_add_u32 v250, v176, 6, v171
	global_load_dwordx4 v[230:233], v250, s[70:71]
	v_add_u32_e32 v176, 3, v174
	v_cmp_gt_u32_e64 s[32:33], s91, v176
	s_nop 1
	v_cndmask_b32_e64 v176, 0, v176, s[32:33]
	v_add_u32_e32 v176, s88, v176
	v_lshl_add_u32 v251, v176, 6, v171
	global_load_dwordx4 v[234:237], v251, s[70:71]
	global_load_dwordx4 v[190:193], v172, s[100:101]
	global_load_dwordx4 v[194:197], v172, s[100:101] offset:16
	global_load_dwordx4 v[198:201], v172, s[100:101] offset:32
	global_load_dwordx4 v[202:205], v172, s[100:101] offset:48
	s_waitcnt vmcnt(7)
;     __device__ __forceinline__ void operator()(const f32x4 (&acc)[2][2][4][2], const Unit& u, int wr, int wc, int fr, int fq) const {
;     ...
;             for (int m = 0; m < 4; ++m) { const int t = tbase + 16 * m + fr; const bool vin = (t >= 0) && (t < slen); const int grow = seqbase + (vin ? t : 0);
;                 const f32x4 p = *(const f32x4*)(PS + (size_t)grow * 16 + 4 * fq); float s = (p[0] + p[1]) + (p[2] + p[3]); s = bfly_add<16>(s); s = bfly_add<32>(s); rs[m] = vin ? rsqrtf(s * (1.f / DM) + EPS) : 0.f; }
;             unsigned outw[4][2][2];
; #pragma unroll
;             for (int n = 0; n < 2; ++n)
; #pragma unroll
;                 for (int jp = 0; jp < 2; ++jp) {
;                     const int cidx = (4 * n + 2 * jp) * 2;
;                     const f32x4 c0a = ct[cidx], c0b = ct[cidx + 1], c1a = ct[cidx + 2], c1b = ct[cidx + 3];
;                     const f32x2 wv0 = {c0a[0], c1a[0]}, wv1 = {c0a[1], c1a[1]}, wv2 = {c0a[2], c1a[2]}, bv = {c0a[3], c1a[3]};
;                     const f32x2 wg0 = {c0b[0], c1b[0]}, wg1 = {c0b[1], c1b[1]}, wg2 = {c0b[2], c1b[2]}, bg = {c0b[3], c1b[3]};
;                     f32x2 uv[4], ug[4], cv[4];
; #pragma unroll
;                     for (int m = 0; m < 4; ++m) { uv[m] = (f32x2){acc[ai][0][m][n][2 * jp], acc[ai][0][m][n][2 * jp + 1]}; ug[m] = (f32x2){acc[ai][1][m][n][2 * jp], acc[ai][1][m][n][2 * jp + 1]}; }
;                     asm volatile("" : "+v"(uv[0]), "+v"(uv[1]), "+v"(uv[2]), "+v"(uv[3]), "+v"(ug[0]), "+v"(ug[1]), "+v"(ug[2]), "+v"(ug[3]));
;                     {
;                         f32x2 rv[4], lv[4];
; #pragma unroll
;                         for (int m = 0; m < 4; ++m) { uv[m] = uv[m] * rs[m]; rv[m] = (f32x2){dpp_ror1(uv[m][0]), dpp_ror1(uv[m][1])}; lv[m] = (f32x2){dpp_ror15(uv[m][0]), dpp_ror15(uv[m][1])}; }
; #pragma unroll
;                         for (int m = 0; m < 4; ++m) { const f32x2 pv_ = (m > 0 && f0) ? rv[m > 0 ? m - 1 : 0] : rv[m], nv_ = (m < 3 && f15) ? lv[m < 3 ? m + 1 : 3] : lv[m];
;                             cv[m] = bv + wv0 * pv_ + wv1 * uv[m] + wv2 * nv_; }
;                     }
;                     asm volatile("" : "+v"(cv[0]), "+v"(cv[1]), "+v"(cv[2]), "+v"(cv[3]));
;                     {
;                         f32x2 rg[4], lg[4];
; #pragma unroll
	v_add_f32_e32 v222, v222, v223
	v_add_f32_e32 v224, v224, v225
	v_add_f32_e32 v222, v222, v224
	v_mov_b32_e32 v223, v222
	s_nop 1
	v_permlane16_swap_b32_e32 v222, v223
	v_add_f32_e32 v222, v222, v223
	v_mov_b32_e32 v223, v222
	s_nop 1
	v_permlane32_swap_b32_e32 v222, v223
	v_add_f32_e32 v222, v222, v223
	v_fma_f32 v222, v222, s82, v252
	v_cmp_gt_f32_e32 vcc, s62, v222
	v_mul_f32_e32 v223, 0x4b800000, v222
	s_nop 0
	v_cndmask_b32_e32 v222, v222, v223, vcc
	v_rsq_f32_e32 v222, v222
	s_nop 0
	v_mul_f32_e32 v223, 0x45800000, v222
	v_cndmask_b32_e32 v222, v222, v223, vcc
	v_cndmask_b32_e64 v178, 0, v222, s[52:53]
	s_waitcnt vmcnt(6)
	v_add_f32_e32 v226, v226, v227
	v_add_f32_e32 v228, v228, v229
	v_add_f32_e32 v226, v226, v228
	v_mov_b32_e32 v227, v226
	s_nop 1
	v_permlane16_swap_b32_e32 v226, v227
	v_add_f32_e32 v226, v226, v227
	v_mov_b32_e32 v227, v226
	s_nop 1
	v_permlane32_swap_b32_e32 v226, v227
	v_add_f32_e32 v226, v226, v227
	v_fma_f32 v226, v226, s82, v252
	v_cmp_gt_f32_e32 vcc, s62, v226
	v_mul_f32_e32 v227, 0x4b800000, v226
	s_nop 0
	v_cndmask_b32_e32 v226, v226, v227, vcc
	v_rsq_f32_e32 v226, v226
	s_nop 0
	v_mul_f32_e32 v227, 0x45800000, v226
	v_cndmask_b32_e32 v226, v226, v227, vcc
	v_cndmask_b32_e64 v180, 0, v226, s[64:65]
	s_waitcnt vmcnt(5)
	v_add_f32_e32 v230, v230, v231
	v_add_f32_e32 v232, v232, v233
	v_add_f32_e32 v230, v230, v232
	v_mov_b32_e32 v231, v230
	s_nop 1
	v_permlane16_swap_b32_e32 v230, v231
	v_add_f32_e32 v230, v230, v231
	v_mov_b32_e32 v231, v230
	s_nop 1
	v_permlane32_swap_b32_e32 v230, v231
	v_add_f32_e32 v230, v230, v231
	v_fma_f32 v230, v230, s82, v252
	v_cmp_gt_f32_e32 vcc, s62, v230
	v_mul_f32_e32 v231, 0x4b800000, v230
	s_nop 0
	v_cndmask_b32_e32 v230, v230, v231, vcc
	v_rsq_f32_e32 v230, v230
	s_nop 0
	v_mul_f32_e32 v231, 0x45800000, v230
	v_cndmask_b32_e32 v230, v230, v231, vcc
	v_cndmask_b32_e64 v182, 0, v230, s[98:99]
	s_waitcnt vmcnt(4)
	v_add_f32_e32 v234, v234, v235
	v_add_f32_e32 v236, v236, v237
	v_add_f32_e32 v234, v234, v236
	v_mov_b32_e32 v235, v234
	s_nop 1
	v_permlane16_swap_b32_e32 v234, v235
	v_add_f32_e32 v234, v234, v235
	v_mov_b32_e32 v235, v234
	s_nop 1
	v_permlane32_swap_b32_e32 v234, v235
	v_add_f32_e32 v234, v234, v235
	v_fma_f32 v234, v234, s82, v252
	v_cmp_gt_f32_e32 vcc, s62, v234
	v_mul_f32_e32 v235, 0x4b800000, v234
	s_nop 0
	v_cndmask_b32_e32 v234, v234, v235, vcc
	v_rsq_f32_e32 v234, v234
	s_nop 0
	v_mul_f32_e32 v235, 0x45800000, v234
	v_cndmask_b32_e32 v234, v234, v235, vcc
	v_cndmask_b32_e64 v144, 0, v234, s[32:33]
	global_load_dwordx4 v[206:209], v172, s[100:101] offset:64
	global_load_dwordx4 v[210:213], v172, s[100:101] offset:80
	global_load_dwordx4 v[214:217], v172, s[100:101] offset:96
	global_load_dwordx4 v[218:221], v172, s[100:101] offset:112
	s_waitcnt vmcnt(4)
	v_pk_mul_f32 v[60:61], v[60:61], v[178:179] op_sel_hi:[1,0]
	v_pk_mul_f32 v[56:57], v[56:57], v[180:181] op_sel_hi:[1,0]
	v_pk_mul_f32 v[52:53], v[52:53], v[182:183] op_sel_hi:[1,0]
	v_pk_mul_f32 v[48:49], v[48:49], v[144:145] op_sel_hi:[1,0]
	v_pk_mul_f32 v[44:45], v[44:45], v[178:179] op_sel_hi:[1,0]
	v_pk_mul_f32 v[40:41], v[40:41], v[180:181] op_sel_hi:[1,0]
	v_pk_mul_f32 v[36:37], v[36:37], v[182:183] op_sel_hi:[1,0]
	v_pk_mul_f32 v[32:33], v[32:33], v[144:145] op_sel_hi:[1,0]
	s_nop 1
	v_mov_b32_dpp v248, v48 row_shr:1 row_mask:0xf bank_mask:0xf bound_ctrl:1
	v_mov_b32_dpp v249, v49 row_shr:1 row_mask:0xf bank_mask:0xf bound_ctrl:1
	v_mov_b32_dpp v250, v60 row_shl:1 row_mask:0xf bank_mask:0xf bound_ctrl:1
	v_mov_b32_dpp v251, v61 row_shl:1 row_mask:0xf bank_mask:0xf bound_ctrl:1
	v_pk_fma_f32 v[224:225], v[190:191], v[248:249], v[196:197]
	v_pk_fma_f32 v[226:227], v[190:191], v[60:61], v[196:197]
	v_pk_fma_f32 v[228:229], v[190:191], v[56:57], v[196:197]
	v_pk_fma_f32 v[230:231], v[190:191], v[52:53], v[196:197]
	v_pk_fma_f32 v[224:225], v[192:193], v[60:61], v[224:225]
	v_pk_fma_f32 v[226:227], v[192:193], v[56:57], v[226:227]
	v_pk_fma_f32 v[228:229], v[192:193], v[52:53], v[228:229]
	v_pk_fma_f32 v[230:231], v[192:193], v[48:49], v[230:231]
	v_pk_fma_f32 v[224:225], v[194:195], v[56:57], v[224:225]
	v_pk_fma_f32 v[226:227], v[194:195], v[52:53], v[226:227]
	v_pk_fma_f32 v[228:229], v[194:195], v[48:49], v[228:229]
	v_pk_fma_f32 v[230:231], v[194:195], v[250:251], v[230:231]
	s_nop 1
	v_mov_b32_dpp v248, v32 row_shr:1 row_mask:0xf bank_mask:0xf bound_ctrl:1
	v_mov_b32_dpp v249, v33 row_shr:1 row_mask:0xf bank_mask:0xf bound_ctrl:1
	v_mov_b32_dpp v250, v44 row_shl:1 row_mask:0xf bank_mask:0xf bound_ctrl:1
	v_mov_b32_dpp v251, v45 row_shl:1 row_mask:0xf bank_mask:0xf bound_ctrl:1
	v_pk_fma_f32 v[232:233], v[198:199], v[248:249], v[204:205]
	v_pk_fma_f32 v[234:235], v[198:199], v[44:45], v[204:205]
	v_pk_fma_f32 v[236:237], v[198:199], v[40:41], v[204:205]
	v_pk_fma_f32 v[238:239], v[198:199], v[36:37], v[204:205]
	v_pk_fma_f32 v[232:233], v[200:201], v[44:45], v[232:233]
	v_pk_fma_f32 v[234:235], v[200:201], v[40:41], v[234:235]
	v_pk_fma_f32 v[236:237], v[200:201], v[36:37], v[236:237]
	v_pk_fma_f32 v[238:239], v[200:201], v[32:33], v[238:239]
	v_pk_fma_f32 v[232:233], v[202:203], v[40:41], v[232:233]
	v_pk_fma_f32 v[234:235], v[202:203], v[36:37], v[234:235]
	v_pk_fma_f32 v[236:237], v[202:203], v[32:33], v[236:237]
	v_pk_fma_f32 v[238:239], v[202:203], v[250:251], v[238:239]
	v_exp_f32_e64 v240, -v232
	v_exp_f32_e64 v241, -v233
	v_exp_f32_e64 v242, -v234
	v_exp_f32_e64 v243, -v235
	v_exp_f32_e64 v244, -v236
	v_exp_f32_e64 v245, -v237
	v_exp_f32_e64 v246, -v238
	v_exp_f32_e64 v247, -v239
	v_pk_mul_f32 v[224:225], v[224:225], v[232:233]
	v_pk_mul_f32 v[226:227], v[226:227], v[234:235]
	v_pk_mul_f32 v[228:229], v[228:229], v[236:237]
	v_pk_mul_f32 v[230:231], v[230:231], v[238:239]
	v_pk_add_f32 v[240:241], v[240:241], 1.0 op_sel_hi:[1,0]
	v_pk_add_f32 v[242:243], v[242:243], 1.0 op_sel_hi:[1,0]
	v_pk_add_f32 v[244:245], v[244:245], 1.0 op_sel_hi:[1,0]
	v_pk_add_f32 v[246:247], v[246:247], 1.0 op_sel_hi:[1,0]
	v_rcp_f32_e32 v240, v240
	v_rcp_f32_e32 v241, v241
	v_rcp_f32_e32 v242, v242
	v_rcp_f32_e32 v243, v243
	v_rcp_f32_e32 v244, v244
	v_rcp_f32_e32 v245, v245
	v_rcp_f32_e32 v246, v246
	v_rcp_f32_e32 v247, v247
	s_nop 0
	v_pk_mul_f32 v[224:225], v[224:225], v[240:241]
	v_pk_mul_f32 v[226:227], v[226:227], v[242:243]
	v_pk_mul_f32 v[228:229], v[228:229], v[244:245]
	v_pk_mul_f32 v[230:231], v[230:231], v[246:247]
	v_cvt_pk_bf16_f32 v128, v224, v225
	v_cvt_pk_bf16_f32 v132, v226, v227
	v_cvt_pk_bf16_f32 v136, v228, v229
	v_cvt_pk_bf16_f32 v140, v230, v231
	global_load_dwordx4 v[190:193], v172, s[100:101] offset:128
	global_load_dwordx4 v[194:197], v172, s[100:101] offset:144
	global_load_dwordx4 v[198:201], v172, s[100:101] offset:160
	global_load_dwordx4 v[202:205], v172, s[100:101] offset:176
	s_waitcnt vmcnt(4)
;     __device__ __forceinline__ void operator()(const f32x4 (&acc)[2][2][4][2], const Unit& u, int wr, int wc, int fr, int fq) const {
;     ...
;             for (int n = 0; n < 2; ++n)
; #pragma unroll
;                 for (int jp = 0; jp < 2; ++jp) {
;                     const int cidx = (4 * n + 2 * jp) * 2;
;                     const f32x4 c0a = ct[cidx], c0b = ct[cidx + 1], c1a = ct[cidx + 2], c1b = ct[cidx + 3];
;                     const f32x2 wv0 = {c0a[0], c1a[0]}, wv1 = {c0a[1], c1a[1]}, wv2 = {c0a[2], c1a[2]}, bv = {c0a[3], c1a[3]};
;                     const f32x2 wg0 = {c0b[0], c1b[0]}, wg1 = {c0b[1], c1b[1]}, wg2 = {c0b[2], c1b[2]}, bg = {c0b[3], c1b[3]};
;                     f32x2 uv[4], ug[4], cv[4];
; #pragma unroll
;                     for (int m = 0; m < 4; ++m) { uv[m] = (f32x2){acc[ai][0][m][n][2 * jp], acc[ai][0][m][n][2 * jp + 1]}; ug[m] = (f32x2){acc[ai][1][m][n][2 * jp], acc[ai][1][m][n][2 * jp + 1]}; }
;                     asm volatile("" : "+v"(uv[0]), "+v"(uv[1]), "+v"(uv[2]), "+v"(uv[3]), "+v"(ug[0]), "+v"(ug[1]), "+v"(ug[2]), "+v"(ug[3]));
;                     {
;                         f32x2 rv[4], lv[4];
; #pragma unroll
;                         for (int m = 0; m < 4; ++m) { uv[m] = uv[m] * rs[m]; rv[m] = (f32x2){dpp_ror1(uv[m][0]), dpp_ror1(uv[m][1])}; lv[m] = (f32x2){dpp_ror15(uv[m][0]), dpp_ror15(uv[m][1])}; }
; #pragma unroll
;                         for (int m = 0; m < 4; ++m) { const f32x2 pv_ = (m > 0 && f0) ? rv[m > 0 ? m - 1 : 0] : rv[m], nv_ = (m < 3 && f15) ? lv[m < 3 ? m + 1 : 3] : lv[m];
;                             cv[m] = bv + wv0 * pv_ + wv1 * uv[m] + wv2 * nv_; }
;                     }
;                     asm volatile("" : "+v"(cv[0]), "+v"(cv[1]), "+v"(cv[2]), "+v"(cv[3]));
;                     {
;                         f32x2 rg[4], lg[4];
; #pragma unroll
;                         for (int m = 0; m < 4; ++m) { ug[m] = ug[m] * rs[m]; rg[m] = (f32x2){dpp_ror1(ug[m][0]), dpp_ror1(ug[m][1])}; lg[m] = (f32x2){dpp_ror15(ug[m][0]), dpp_ror15(ug[m][1])}; }
; #pragma unroll
;                         for (int m = 0; m < 4; ++m) { const f32x2 pg_ = (m > 0 && f0) ? rg[m > 0 ? m - 1 : 0] : rg[m], ng_ = (m < 3 && f15) ? lg[m < 3 ? m + 1 : 3] : lg[m];
;                             const f32x2 cgt = bg + wg0 * pg_ + wg1 * ug[m] + wg2 * ng_;
;                             const f32x2 e = cgt * (-LOG2E);
	v_pk_mul_f32 v[62:63], v[62:63], v[178:179] op_sel_hi:[1,0]
	v_pk_mul_f32 v[58:59], v[58:59], v[180:181] op_sel_hi:[1,0]
	v_pk_mul_f32 v[54:55], v[54:55], v[182:183] op_sel_hi:[1,0]
	v_pk_mul_f32 v[50:51], v[50:51], v[144:145] op_sel_hi:[1,0]
	v_pk_mul_f32 v[46:47], v[46:47], v[178:179] op_sel_hi:[1,0]
	v_pk_mul_f32 v[42:43], v[42:43], v[180:181] op_sel_hi:[1,0]
	v_pk_mul_f32 v[38:39], v[38:39], v[182:183] op_sel_hi:[1,0]
	v_pk_mul_f32 v[34:35], v[34:35], v[144:145] op_sel_hi:[1,0]
	s_nop 1
	v_mov_b32_dpp v248, v50 row_shr:1 row_mask:0xf bank_mask:0xf bound_ctrl:1
	v_mov_b32_dpp v249, v51 row_shr:1 row_mask:0xf bank_mask:0xf bound_ctrl:1
	v_mov_b32_dpp v250, v62 row_shl:1 row_mask:0xf bank_mask:0xf bound_ctrl:1
	v_mov_b32_dpp v251, v63 row_shl:1 row_mask:0xf bank_mask:0xf bound_ctrl:1
	v_pk_fma_f32 v[224:225], v[206:207], v[248:249], v[212:213]
	v_pk_fma_f32 v[226:227], v[206:207], v[62:63], v[212:213]
	v_pk_fma_f32 v[228:229], v[206:207], v[58:59], v[212:213]
	v_pk_fma_f32 v[230:231], v[206:207], v[54:55], v[212:213]
	v_pk_fma_f32 v[224:225], v[208:209], v[62:63], v[224:225]
	v_pk_fma_f32 v[226:227], v[208:209], v[58:59], v[226:227]
	v_pk_fma_f32 v[228:229], v[208:209], v[54:55], v[228:229]
	v_pk_fma_f32 v[230:231], v[208:209], v[50:51], v[230:231]
	v_pk_fma_f32 v[224:225], v[210:211], v[58:59], v[224:225]
	v_pk_fma_f32 v[226:227], v[210:211], v[54:55], v[226:227]
	v_pk_fma_f32 v[228:229], v[210:211], v[50:51], v[228:229]
	v_pk_fma_f32 v[230:231], v[210:211], v[250:251], v[230:231]
	s_nop 1
	v_mov_b32_dpp v248, v34 row_shr:1 row_mask:0xf bank_mask:0xf bound_ctrl:1
	v_mov_b32_dpp v249, v35 row_shr:1 row_mask:0xf bank_mask:0xf bound_ctrl:1
	v_mov_b32_dpp v250, v46 row_shl:1 row_mask:0xf bank_mask:0xf bound_ctrl:1
	v_mov_b32_dpp v251, v47 row_shl:1 row_mask:0xf bank_mask:0xf bound_ctrl:1
	v_pk_fma_f32 v[232:233], v[214:215], v[248:249], v[220:221]
	v_pk_fma_f32 v[234:235], v[214:215], v[46:47], v[220:221]
	v_pk_fma_f32 v[236:237], v[214:215], v[42:43], v[220:221]
	v_pk_fma_f32 v[238:239], v[214:215], v[38:39], v[220:221]
	v_pk_fma_f32 v[232:233], v[216:217], v[46:47], v[232:233]
	v_pk_fma_f32 v[234:235], v[216:217], v[42:43], v[234:235]
	v_pk_fma_f32 v[236:237], v[216:217], v[38:39], v[236:237]
	v_pk_fma_f32 v[238:239], v[216:217], v[34:35], v[238:239]
	v_pk_fma_f32 v[232:233], v[218:219], v[42:43], v[232:233]
	v_pk_fma_f32 v[234:235], v[218:219], v[38:39], v[234:235]
	v_pk_fma_f32 v[236:237], v[218:219], v[34:35], v[236:237]
	v_pk_fma_f32 v[238:239], v[218:219], v[250:251], v[238:239]
	v_exp_f32_e64 v240, -v232
	v_exp_f32_e64 v241, -v233
	v_exp_f32_e64 v242, -v234
	v_exp_f32_e64 v243, -v235
	v_exp_f32_e64 v244, -v236
	v_exp_f32_e64 v245, -v237
	v_exp_f32_e64 v246, -v238
	v_exp_f32_e64 v247, -v239
	v_pk_mul_f32 v[224:225], v[224:225], v[232:233]
	v_pk_mul_f32 v[226:227], v[226:227], v[234:235]
	v_pk_mul_f32 v[228:229], v[228:229], v[236:237]
	v_pk_mul_f32 v[230:231], v[230:231], v[238:239]
	v_pk_add_f32 v[240:241], v[240:241], 1.0 op_sel_hi:[1,0]
	v_pk_add_f32 v[242:243], v[242:243], 1.0 op_sel_hi:[1,0]
	v_pk_add_f32 v[244:245], v[244:245], 1.0 op_sel_hi:[1,0]
	v_pk_add_f32 v[246:247], v[246:247], 1.0 op_sel_hi:[1,0]
	v_rcp_f32_e32 v240, v240
	v_rcp_f32_e32 v241, v241
	v_rcp_f32_e32 v242, v242
	v_rcp_f32_e32 v243, v243
	v_rcp_f32_e32 v244, v244
	v_rcp_f32_e32 v245, v245
	v_rcp_f32_e32 v246, v246
	v_rcp_f32_e32 v247, v247
	s_nop 0
	v_pk_mul_f32 v[224:225], v[224:225], v[240:241]
	v_pk_mul_f32 v[226:227], v[226:227], v[242:243]
	v_pk_mul_f32 v[228:229], v[228:229], v[244:245]
	v_pk_mul_f32 v[230:231], v[230:231], v[246:247]
	v_cvt_pk_bf16_f32 v129, v224, v225
	v_cvt_pk_bf16_f32 v133, v226, v227
	v_cvt_pk_bf16_f32 v137, v228, v229
	v_cvt_pk_bf16_f32 v141, v230, v231
	global_load_dwordx4 v[206:209], v172, s[100:101] offset:192
	global_load_dwordx4 v[210:213], v172, s[100:101] offset:208
	global_load_dwordx4 v[214:217], v172, s[100:101] offset:224
	global_load_dwordx4 v[218:221], v172, s[100:101] offset:240
	s_waitcnt vmcnt(4)
	v_pk_mul_f32 v[28:29], v[28:29], v[178:179] op_sel_hi:[1,0]
	v_pk_mul_f32 v[24:25], v[24:25], v[180:181] op_sel_hi:[1,0]
	v_pk_mul_f32 v[20:21], v[20:21], v[182:183] op_sel_hi:[1,0]
	v_pk_mul_f32 v[16:17], v[16:17], v[144:145] op_sel_hi:[1,0]
	v_pk_mul_f32 v[12:13], v[12:13], v[178:179] op_sel_hi:[1,0]
	v_pk_mul_f32 v[8:9], v[8:9], v[180:181] op_sel_hi:[1,0]
	v_pk_mul_f32 v[4:5], v[4:5], v[182:183] op_sel_hi:[1,0]
	v_pk_mul_f32 v[0:1], v[0:1], v[144:145] op_sel_hi:[1,0]
	s_nop 1
	v_mov_b32_dpp v248, v16 row_shr:1 row_mask:0xf bank_mask:0xf bound_ctrl:1
	v_mov_b32_dpp v249, v17 row_shr:1 row_mask:0xf bank_mask:0xf bound_ctrl:1
	v_mov_b32_dpp v250, v28 row_shl:1 row_mask:0xf bank_mask:0xf bound_ctrl:1
	v_mov_b32_dpp v251, v29 row_shl:1 row_mask:0xf bank_mask:0xf bound_ctrl:1
	v_pk_fma_f32 v[224:225], v[190:191], v[248:249], v[196:197]
	v_pk_fma_f32 v[226:227], v[190:191], v[28:29], v[196:197]
	v_pk_fma_f32 v[228:229], v[190:191], v[24:25], v[196:197]
	v_pk_fma_f32 v[230:231], v[190:191], v[20:21], v[196:197]
	v_pk_fma_f32 v[224:225], v[192:193], v[28:29], v[224:225]
	v_pk_fma_f32 v[226:227], v[192:193], v[24:25], v[226:227]
	v_pk_fma_f32 v[228:229], v[192:193], v[20:21], v[228:229]
	v_pk_fma_f32 v[230:231], v[192:193], v[16:17], v[230:231]
	v_pk_fma_f32 v[224:225], v[194:195], v[24:25], v[224:225]
	v_pk_fma_f32 v[226:227], v[194:195], v[20:21], v[226:227]
	v_pk_fma_f32 v[228:229], v[194:195], v[16:17], v[228:229]
	v_pk_fma_f32 v[230:231], v[194:195], v[250:251], v[230:231]
	s_nop 1
	v_mov_b32_dpp v248, v0 row_shr:1 row_mask:0xf bank_mask:0xf bound_ctrl:1
	v_mov_b32_dpp v249, v1 row_shr:1 row_mask:0xf bank_mask:0xf bound_ctrl:1
;     __device__ __forceinline__ void operator()(const f32x4 (&acc)[2][2][4][2], const Unit& u, int wr, int wc, int fr, int fq) const {
;     ...
;                         for (int m = 0; m < 4; ++m) { uv[m] = uv[m] * rs[m]; rv[m] = (f32x2){dpp_ror1(uv[m][0]), dpp_ror1(uv[m][1])}; lv[m] = (f32x2){dpp_ror15(uv[m][0]), dpp_ror15(uv[m][1])}; }
; #pragma unroll
;                         for (int m = 0; m < 4; ++m) { const f32x2 pv_ = (m > 0 && f0) ? rv[m > 0 ? m - 1 : 0] : rv[m], nv_ = (m < 3 && f15) ? lv[m < 3 ? m + 1 : 3] : lv[m];
;                             cv[m] = bv + wv0 * pv_ + wv1 * uv[m] + wv2 * nv_; }
;                     }
;                     asm volatile("" : "+v"(cv[0]), "+v"(cv[1]), "+v"(cv[2]), "+v"(cv[3]));
;                     {
;                         f32x2 rg[4], lg[4];
; #pragma unroll
;                         for (int m = 0; m < 4; ++m) { ug[m] = ug[m] * rs[m]; rg[m] = (f32x2){dpp_ror1(ug[m][0]), dpp_ror1(ug[m][1])}; lg[m] = (f32x2){dpp_ror15(ug[m][0]), dpp_ror15(ug[m][1])}; }
; #pragma unroll
;                         for (int m = 0; m < 4; ++m) { const f32x2 pg_ = (m > 0 && f0) ? rg[m > 0 ? m - 1 : 0] : rg[m], ng_ = (m < 3 && f15) ? lg[m < 3 ? m + 1 : 3] : lg[m];
;                             const f32x2 cgt = bg + wg0 * pg_ + wg1 * ug[m] + wg2 * ng_;
;                             const f32x2 e = cgt * (-LOG2E);
;                             const f32x2 d = (f32x2){__builtin_amdgcn_exp2f(e[0]), __builtin_amdgcn_exp2f(e[1])} + 1.f;
;                             const f32x2 sg = {__builtin_amdgcn_rcpf(d[0]), __builtin_amdgcn_rcpf(d[1])};
;                             const f32x2 ov = cv[m] * cgt * sg;
;                             outw[m][n][jp] = cvtpk(ov[0], ov[1]); }
;                     }
;                     asm volatile("" : "+v"(outw[0][n][jp]), "+v"(outw[1][n][jp]), "+v"(outw[2][n][jp]), "+v"(outw[3][n][jp]) :: "memory"); __builtin_amdgcn_sched_barrier(0);
;                 }
; #pragma unroll
;             for (int m = 0; m < 4; ++m) { const int i = 16 * m + fr, t = tbase + i;
;                 if (i >= 1 && i <= 62 && t < slen) { u32x4 w; w.x = outw[m][0][0]; w.y = outw[m][0][1]; w.z = outw[m][1][0]; w.w = outw[m][1][1];
;                     *(u32x4*)(Gout + (size_t)(seqbase + t) * DFF + 128 * u.pn + 32 * wc + 8 * fq) = w; } }
	v_mov_b32_dpp v250, v12 row_shl:1 row_mask:0xf bank_mask:0xf bound_ctrl:1
	v_mov_b32_dpp v251, v13 row_shl:1 row_mask:0xf bank_mask:0xf bound_ctrl:1
	v_pk_fma_f32 v[232:233], v[198:199], v[248:249], v[204:205]
	v_pk_fma_f32 v[234:235], v[198:199], v[12:13], v[204:205]
	v_pk_fma_f32 v[236:237], v[198:199], v[8:9], v[204:205]
	v_pk_fma_f32 v[238:239], v[198:199], v[4:5], v[204:205]
	v_pk_fma_f32 v[232:233], v[200:201], v[12:13], v[232:233]
	v_pk_fma_f32 v[234:235], v[200:201], v[8:9], v[234:235]
	v_pk_fma_f32 v[236:237], v[200:201], v[4:5], v[236:237]
	v_pk_fma_f32 v[238:239], v[200:201], v[0:1], v[238:239]
	v_pk_fma_f32 v[232:233], v[202:203], v[8:9], v[232:233]
	v_pk_fma_f32 v[234:235], v[202:203], v[4:5], v[234:235]
	v_pk_fma_f32 v[236:237], v[202:203], v[0:1], v[236:237]
	v_pk_fma_f32 v[238:239], v[202:203], v[250:251], v[238:239]
	v_exp_f32_e64 v240, -v232
	v_exp_f32_e64 v241, -v233
	v_exp_f32_e64 v242, -v234
	v_exp_f32_e64 v243, -v235
	v_exp_f32_e64 v244, -v236
	v_exp_f32_e64 v245, -v237
	v_exp_f32_e64 v246, -v238
	v_exp_f32_e64 v247, -v239
	v_pk_mul_f32 v[224:225], v[224:225], v[232:233]
	v_pk_mul_f32 v[226:227], v[226:227], v[234:235]
	v_pk_mul_f32 v[228:229], v[228:229], v[236:237]
	v_pk_mul_f32 v[230:231], v[230:231], v[238:239]
	v_pk_add_f32 v[240:241], v[240:241], 1.0 op_sel_hi:[1,0]
	v_pk_add_f32 v[242:243], v[242:243], 1.0 op_sel_hi:[1,0]
	v_pk_add_f32 v[244:245], v[244:245], 1.0 op_sel_hi:[1,0]
	v_pk_add_f32 v[246:247], v[246:247], 1.0 op_sel_hi:[1,0]
	v_rcp_f32_e32 v240, v240
	v_rcp_f32_e32 v241, v241
	v_rcp_f32_e32 v242, v242
	v_rcp_f32_e32 v243, v243
	v_rcp_f32_e32 v244, v244
	v_rcp_f32_e32 v245, v245
	v_rcp_f32_e32 v246, v246
	v_rcp_f32_e32 v247, v247
	s_nop 0
	v_pk_mul_f32 v[224:225], v[224:225], v[240:241]
	v_pk_mul_f32 v[226:227], v[226:227], v[242:243]
	v_pk_mul_f32 v[228:229], v[228:229], v[244:245]
	v_pk_mul_f32 v[230:231], v[230:231], v[246:247]
	v_cvt_pk_bf16_f32 v130, v224, v225
	v_cvt_pk_bf16_f32 v134, v226, v227
	v_cvt_pk_bf16_f32 v138, v228, v229
	v_cvt_pk_bf16_f32 v142, v230, v231
	s_waitcnt vmcnt(0)
	v_pk_mul_f32 v[30:31], v[30:31], v[178:179] op_sel_hi:[1,0]
	v_pk_mul_f32 v[26:27], v[26:27], v[180:181] op_sel_hi:[1,0]
	v_pk_mul_f32 v[22:23], v[22:23], v[182:183] op_sel_hi:[1,0]
	v_pk_mul_f32 v[18:19], v[18:19], v[144:145] op_sel_hi:[1,0]
	v_pk_mul_f32 v[14:15], v[14:15], v[178:179] op_sel_hi:[1,0]
	v_pk_mul_f32 v[10:11], v[10:11], v[180:181] op_sel_hi:[1,0]
	v_pk_mul_f32 v[6:7], v[6:7], v[182:183] op_sel_hi:[1,0]
	v_pk_mul_f32 v[2:3], v[2:3], v[144:145] op_sel_hi:[1,0]
	s_nop 1
	v_mov_b32_dpp v248, v18 row_shr:1 row_mask:0xf bank_mask:0xf bound_ctrl:1
	v_mov_b32_dpp v249, v19 row_shr:1 row_mask:0xf bank_mask:0xf bound_ctrl:1
	v_mov_b32_dpp v250, v30 row_shl:1 row_mask:0xf bank_mask:0xf bound_ctrl:1
	v_mov_b32_dpp v251, v31 row_shl:1 row_mask:0xf bank_mask:0xf bound_ctrl:1
	v_pk_fma_f32 v[224:225], v[206:207], v[248:249], v[212:213]
	v_pk_fma_f32 v[226:227], v[206:207], v[30:31], v[212:213]
	v_pk_fma_f32 v[228:229], v[206:207], v[26:27], v[212:213]
	v_pk_fma_f32 v[230:231], v[206:207], v[22:23], v[212:213]
	v_pk_fma_f32 v[224:225], v[208:209], v[30:31], v[224:225]
	v_pk_fma_f32 v[226:227], v[208:209], v[26:27], v[226:227]
	v_pk_fma_f32 v[228:229], v[208:209], v[22:23], v[228:229]
	v_pk_fma_f32 v[230:231], v[208:209], v[18:19], v[230:231]
	v_pk_fma_f32 v[224:225], v[210:211], v[26:27], v[224:225]
	v_pk_fma_f32 v[226:227], v[210:211], v[22:23], v[226:227]
	v_pk_fma_f32 v[228:229], v[210:211], v[18:19], v[228:229]
	v_pk_fma_f32 v[230:231], v[210:211], v[250:251], v[230:231]
	s_nop 1
	v_mov_b32_dpp v248, v2 row_shr:1 row_mask:0xf bank_mask:0xf bound_ctrl:1
	v_mov_b32_dpp v249, v3 row_shr:1 row_mask:0xf bank_mask:0xf bound_ctrl:1
	v_mov_b32_dpp v250, v14 row_shl:1 row_mask:0xf bank_mask:0xf bound_ctrl:1
	v_mov_b32_dpp v251, v15 row_shl:1 row_mask:0xf bank_mask:0xf bound_ctrl:1
	v_pk_fma_f32 v[232:233], v[214:215], v[248:249], v[220:221]
	v_pk_fma_f32 v[234:235], v[214:215], v[14:15], v[220:221]
	v_pk_fma_f32 v[236:237], v[214:215], v[10:11], v[220:221]
	v_pk_fma_f32 v[238:239], v[214:215], v[6:7], v[220:221]
	v_pk_fma_f32 v[232:233], v[216:217], v[14:15], v[232:233]
	v_pk_fma_f32 v[234:235], v[216:217], v[10:11], v[234:235]
	v_pk_fma_f32 v[236:237], v[216:217], v[6:7], v[236:237]
	v_pk_fma_f32 v[238:239], v[216:217], v[2:3], v[238:239]
	v_pk_fma_f32 v[232:233], v[218:219], v[10:11], v[232:233]
	v_pk_fma_f32 v[234:235], v[218:219], v[6:7], v[234:235]
	v_pk_fma_f32 v[236:237], v[218:219], v[2:3], v[236:237]
	v_pk_fma_f32 v[238:239], v[218:219], v[250:251], v[238:239]
	v_exp_f32_e64 v240, -v232
	v_exp_f32_e64 v241, -v233
	v_exp_f32_e64 v242, -v234
	v_exp_f32_e64 v243, -v235
	v_exp_f32_e64 v244, -v236
	v_exp_f32_e64 v245, -v237
	v_exp_f32_e64 v246, -v238
	v_exp_f32_e64 v247, -v239
	v_pk_mul_f32 v[224:225], v[224:225], v[232:233]
	v_pk_mul_f32 v[226:227], v[226:227], v[234:235]
	v_pk_mul_f32 v[228:229], v[228:229], v[236:237]
	v_pk_mul_f32 v[230:231], v[230:231], v[238:239]
	v_pk_add_f32 v[240:241], v[240:241], 1.0 op_sel_hi:[1,0]
	v_pk_add_f32 v[242:243], v[242:243], 1.0 op_sel_hi:[1,0]
	v_pk_add_f32 v[244:245], v[244:245], 1.0 op_sel_hi:[1,0]
	v_pk_add_f32 v[246:247], v[246:247], 1.0 op_sel_hi:[1,0]
	v_rcp_f32_e32 v240, v240
	v_rcp_f32_e32 v241, v241
	v_rcp_f32_e32 v242, v242
	v_rcp_f32_e32 v243, v243
	v_rcp_f32_e32 v244, v244
	v_rcp_f32_e32 v245, v245
	v_rcp_f32_e32 v246, v246
	v_rcp_f32_e32 v247, v247
	s_nop 0
	v_pk_mul_f32 v[224:225], v[224:225], v[240:241]
	v_pk_mul_f32 v[226:227], v[226:227], v[242:243]
	v_pk_mul_f32 v[228:229], v[228:229], v[244:245]
	v_pk_mul_f32 v[230:231], v[230:231], v[246:247]
	v_cvt_pk_bf16_f32 v131, v224, v225
	v_cvt_pk_bf16_f32 v135, v226, v227
	v_cvt_pk_bf16_f32 v139, v228, v229
	v_cvt_pk_bf16_f32 v143, v230, v231
	v_add_u32_e32 v176, 0, v174
	v_cmp_gt_u32_e32 vcc, s91, v176
	v_cmp_ne_u32_e64 s[52:53], 0, v170
	s_and_b64 vcc, vcc, s[52:53]
	v_add_u32_e32 v176, s88, v176
	v_mad_u32_u24 v248, v176, s54, v171
	s_and_saveexec_b64 s[64:65], vcc
	global_store_dwordx4 v248, v[128:131], s[86:87]
	s_mov_b64 exec, s[64:65]
	v_add_u32_e32 v176, 1, v174
	v_cmp_gt_u32_e32 vcc, s91, v176
	v_add_u32_e32 v176, s88, v176
	v_mad_u32_u24 v249, v176, s54, v171
	s_and_saveexec_b64 s[64:65], vcc
	global_store_dwordx4 v249, v[132:135], s[86:87]
	s_mov_b64 exec, s[64:65]
	v_add_u32_e32 v176, 2, v174
	v_cmp_gt_u32_e32 vcc, s91, v176
	v_add_u32_e32 v176, s88, v176
	v_mad_u32_u24 v250, v176, s54, v171
	s_and_saveexec_b64 s[64:65], vcc
	global_store_dwordx4 v250, v[136:139], s[86:87]
	s_mov_b64 exec, s[64:65]
	v_add_u32_e32 v176, 3, v174
	v_cmp_gt_u32_e32 vcc, s91, v176
	v_cmp_ne_u32_e64 s[52:53], 60, v170
	s_and_b64 vcc, vcc, s[52:53]
	v_add_u32_e32 v176, s88, v176
	v_mad_u32_u24 v251, v176, s54, v171
	s_and_saveexec_b64 s[64:65], vcc
	global_store_dwordx4 v251, v[140:143], s[86:87]
	s_mov_b64 exec, s[64:65]
	s_mov_b64 s[2:3], exec
